# rmsnorm+modulate loops: per-chunk modulation loads hoisted above the chunk stores (renamed live ranges, recomputed vmcnt); GEMM preheader address regs derived from each other
# speedup vs baseline: 1.1309x; 1.0124x over previous
.LBB0_218:
	s_or_b64 exec, exec, s[2:3]
	v_lshlrev_b32_e32 v4, 2, v4
	v_and_b32_e32 v96, 0xfc, v4
	v_lshlrev_b32_e32 v34, 2, v96
	v_lshl_add_u64 v[6:7], v[2:3], 0, v[34:35]
	v_add_co_u32_e64 v40, s[2:3], s29, v6
	global_load_dwordx4 v[26:29], v[6:7], off
	global_load_dwordx4 v[14:17], v[6:7], off offset:1024
	global_load_dwordx4 v[10:13], v[6:7], off offset:2048
	global_load_dwordx4 v[2:5], v[6:7], off offset:3072
	v_addc_co_u32_e64 v41, s[2:3], 0, v7, s[2:3]
	global_load_dwordx4 v[30:33], v[40:41], off
	global_load_dwordx4 v[22:25], v[40:41], off offset:1024
	global_load_dwordx4 v[18:21], v[40:41], off offset:2048
	global_load_dwordx4 v[6:9], v[40:41], off offset:3072
	v_ashrrev_i32_e32 v40, 11, v37
	s_load_dwordx2 s[24:25], s[16:17], 0x48
	v_cmp_lt_i32_e64 s[2:3], v46, v45
	v_mad_i32_i24 v40, v40, s28, s28
	v_cndmask_b32_e64 v40, v40, 0, vcc
	v_cndmask_b32_e64 v41, v44, v46, s[2:3]
	v_lshlrev_b32_e32 v97, 2, v41
	v_ashrrev_i32_e32 v41, 31, v40
	v_lshl_add_u64 v[40:41], v[40:41], 2, s[8:9]
	v_lshl_add_u64 v[42:43], v[40:41], 0, s[22:23]
	v_lshl_add_u64 v[40:41], v[40:41], 0, v[34:35]
	s_waitcnt lgkmcnt(0)
	global_load_dwordx4 v[52:55], v34, s[24:25]
	v_lshl_add_u64 v[64:65], v[42:43], 0, v[34:35]
	global_load_dwordx4 v[56:59], v[40:41], off
	global_load_dwordx4 v[60:63], v[64:65], off
	v_or_b32_e32 v100, 0x400, v34
	v_mov_b32_e32 v101, v35
	v_lshl_add_u64 v[102:103], v[42:43], 0, v[100:101]
	global_load_dwordx4 v[104:107], v[102:103], off
	global_load_dwordx4 v[108:111], v34, s[24:25] offset:1024
	global_load_dwordx4 v[112:115], v[40:41], off offset:1024
	v_mov_b32_e32 v103, v35
	v_or_b32_e32 v102, 0x800, v34
	v_lshl_add_u64 v[102:103], v[42:43], 0, v[102:103]
	global_load_dwordx4 v[116:119], v[102:103], off
	global_load_dwordx4 v[120:123], v34, s[24:25] offset:2048
	global_load_dwordx4 v[124:127], v[40:41], off offset:2048
	global_load_dwordx4 v[128:131], v34, s[24:25] offset:3072
	v_or_b32_e32 v132, 0xc00, v34
	v_mov_b32_e32 v133, v35
	v_lshl_add_u64 v[134:135], v[42:43], 0, v[132:133]
	global_load_dwordx4 v[136:139], v[134:135], off
	global_load_dwordx4 v[140:143], v[40:41], off offset:3072
	v_cmp_lt_i32_e32 vcc, v47, v45
	v_lshlrev_b64 v[38:39], 11, v[38:39]
	v_lshl_add_u64 v[38:39], s[12:13], 0, v[38:39]
	v_add_u32_e32 v1, s11, v1
	s_waitcnt vmcnt(19)
	v_mov_b32_e32 v66, v27
	s_waitcnt vmcnt(18)
	v_mov_b32_e32 v67, v15
	v_mov_b32_e32 v64, v26
	v_mov_b32_e32 v65, v14
	s_waitcnt vmcnt(17)
	v_mov_b32_e32 v74, v11
	s_waitcnt vmcnt(16)
	v_mov_b32_e32 v75, v3
	v_pk_mul_f32 v[66:67], v[66:67], v[66:67]
	s_waitcnt vmcnt(15)
	v_mov_b32_e32 v82, v31
	s_waitcnt vmcnt(14)
	v_mov_b32_e32 v83, v23
	v_mov_b32_e32 v72, v10
	v_mov_b32_e32 v73, v2
	v_mov_b32_e32 v80, v30
	v_mov_b32_e32 v81, v22
	v_pk_mul_f32 v[74:75], v[74:75], v[74:75]
	s_waitcnt vmcnt(13)
	v_mov_b32_e32 v90, v19
	s_waitcnt vmcnt(12)
	v_mov_b32_e32 v91, v7
	v_pk_fma_f32 v[64:65], v[64:65], v[64:65], v[66:67]
	v_pk_mul_f32 v[66:67], v[82:83], v[82:83]
	v_mov_b32_e32 v68, v28
	v_mov_b32_e32 v69, v16
	v_mov_b32_e32 v76, v12
	v_mov_b32_e32 v77, v4
	v_mov_b32_e32 v84, v32
	v_mov_b32_e32 v85, v24
	v_mov_b32_e32 v88, v18
	v_mov_b32_e32 v89, v6
	v_pk_fma_f32 v[72:73], v[72:73], v[72:73], v[74:75]
	v_pk_mul_f32 v[74:75], v[90:91], v[90:91]
	v_pk_fma_f32 v[66:67], v[80:81], v[80:81], v[66:67]
	v_mov_b32_e32 v70, v29
	v_mov_b32_e32 v71, v17
	v_mov_b32_e32 v86, v33
	v_mov_b32_e32 v87, v25
	v_mov_b32_e32 v92, v20
	v_mov_b32_e32 v93, v8
	v_pk_fma_f32 v[64:65], v[68:69], v[68:69], v[64:65]
	v_pk_fma_f32 v[68:69], v[76:77], v[76:77], v[72:73]
	v_pk_fma_f32 v[72:73], v[88:89], v[88:89], v[74:75]
	v_pk_fma_f32 v[66:67], v[84:85], v[84:85], v[66:67]
	v_mov_b32_e32 v78, v13
	v_mov_b32_e32 v79, v5
	v_mov_b32_e32 v94, v21
	v_mov_b32_e32 v95, v9
	v_pk_fma_f32 v[64:65], v[70:71], v[70:71], v[64:65]
	v_pk_fma_f32 v[70:71], v[92:93], v[92:93], v[72:73]
	v_pk_fma_f32 v[66:67], v[86:87], v[86:87], v[66:67]
	v_pk_fma_f32 v[68:69], v[78:79], v[78:79], v[68:69]
	v_pk_fma_f32 v[70:71], v[94:95], v[94:95], v[70:71]
	v_mov_b32_e32 v73, v64
	v_mov_b32_e32 v72, v66
	v_mov_b32_e32 v64, v67
	v_mov_b32_e32 v75, v68
	v_mov_b32_e32 v74, v70
	v_pk_add_f32 v[64:65], v[72:73], v[64:65]
	v_mov_b32_e32 v68, v71
	v_pk_add_f32 v[64:65], v[64:65], v[74:75]
	s_waitcnt vmcnt(9)
	v_add_f32_e32 v60, 1.0, v60
	v_pk_add_f32 v[64:65], v[64:65], v[68:69]
	ds_bpermute_b32 v67, v97, v65
	ds_bpermute_b32 v66, v97, v64
	v_cndmask_b32_e32 v68, v44, v47, vcc
	v_lshlrev_b32_e32 v68, 2, v68
	v_cmp_lt_i32_e32 vcc, v48, v45
	v_mul_f32_e32 v52, v52, v60
	s_waitcnt lgkmcnt(0)
	v_pk_add_f32 v[64:65], v[64:65], v[66:67]
	ds_bpermute_b32 v67, v68, v65
	ds_bpermute_b32 v66, v68, v64
	v_cndmask_b32_e32 v68, v44, v48, vcc
	v_lshlrev_b32_e32 v68, 2, v68
	v_cmp_lt_i32_e32 vcc, v49, v45
	v_add_f32_e32 v61, 1.0, v61
	s_waitcnt lgkmcnt(0)
	v_pk_add_f32 v[64:65], v[64:65], v[66:67]
	ds_bpermute_b32 v67, v68, v65
	ds_bpermute_b32 v66, v68, v64
	v_cndmask_b32_e32 v68, v44, v49, vcc
	v_lshlrev_b32_e32 v68, 2, v68
	v_cmp_lt_i32_e32 vcc, v50, v45
	v_mul_f32_e32 v53, v53, v61
	s_waitcnt lgkmcnt(0)
	v_pk_add_f32 v[64:65], v[64:65], v[66:67]
	ds_bpermute_b32 v67, v68, v65
	ds_bpermute_b32 v66, v68, v64
	v_cndmask_b32_e32 v68, v44, v50, vcc
	v_lshlrev_b32_e32 v68, 2, v68
	v_cmp_lt_i32_e32 vcc, v51, v45
	v_add_f32_e32 v61, 1.0, v62
	s_waitcnt lgkmcnt(0)
	v_pk_add_f32 v[64:65], v[64:65], v[66:67]
	ds_bpermute_b32 v67, v68, v65
	ds_bpermute_b32 v66, v68, v64
	v_cndmask_b32_e32 v68, v44, v51, vcc
	v_lshlrev_b32_e32 v68, 2, v68
	v_mul_f32_e32 v54, v54, v61
	v_add_f32_e32 v61, 1.0, v63
	s_waitcnt lgkmcnt(0)
	v_pk_add_f32 v[64:65], v[64:65], v[66:67]
	ds_bpermute_b32 v67, v68, v65
	ds_bpermute_b32 v66, v68, v64
	v_mul_f32_e32 v55, v55, v61
	s_waitcnt lgkmcnt(0)
	v_pk_add_f32 v[64:65], v[64:65], v[66:67]
	s_nop 0
	v_pk_fma_f32 v[64:65], v[64:65], s[20:21], v[36:37] op_sel_hi:[1,0,0]
	v_add_u32_e32 v37, s21, v37
	v_mul_f32_e32 v66, 0x4b800000, v65
	v_cmp_gt_f32_e32 vcc, s30, v65
	v_mul_f32_e32 v67, 0x4b800000, v64
	v_cmp_gt_f32_e64 s[2:3], s30, v64
	v_cndmask_b32_e32 v65, v65, v66, vcc
	v_rsq_f32_e32 v65, v65
	v_cndmask_b32_e64 v64, v64, v67, s[2:3]
	v_rsq_f32_e32 v64, v64
	v_mul_f32_e32 v60, 0x45800000, v65
	v_cndmask_b32_e32 v60, v65, v60, vcc
	v_mul_f32_e32 v26, v26, v60
	v_mul_f32_e32 v27, v27, v60
	v_fma_f32 v26, v26, v52, v56
	v_fma_f32 v27, v27, v53, v57
	v_mul_f32_e32 v66, 0x45800000, v64
	v_cvt_pk_bf16_f32 v26, v26, v27
	v_mul_f32_e32 v27, v28, v60
	v_mul_f32_e32 v28, v29, v60
	v_cndmask_b32_e64 v64, v64, v66, s[2:3]
	v_fma_f32 v27, v27, v54, v58
	v_fma_f32 v28, v28, v55, v59
	v_cvt_pk_bf16_f32 v27, v27, v28
	v_mul_f32_e32 v28, v30, v64
	v_mul_f32_e32 v29, v31, v64
	v_fma_f32 v28, v28, v52, v56
	v_fma_f32 v29, v29, v53, v57
	v_mul_f32_e32 v30, v33, v64
	v_cvt_pk_bf16_f32 v28, v28, v29
	v_mul_f32_e32 v29, v32, v64
	v_fmac_f32_e32 v59, v30, v55
	v_lshlrev_b32_e32 v30, 1, v96
	v_mov_b32_e32 v31, v35
	v_fma_f32 v29, v29, v54, v58
	v_lshl_add_u64 v[38:39], v[38:39], 0, v[30:31]
	v_cvt_pk_bf16_f32 v29, v29, v59
	global_store_dwordx2 v[38:39], v[26:27], off
	global_store_dwordx2 v[38:39], v[28:29], off offset:2048
	v_or_b32_e32 v26, 0x400, v34
	v_mov_b32_e32 v27, v35
	v_lshl_add_u64 v[56:57], v[42:43], 0, v[26:27]
	v_mul_f32_e32 v14, v14, v60
	v_mul_f32_e32 v15, v15, v60
	v_mul_f32_e32 v16, v16, v60
	v_mul_f32_e32 v17, v17, v60
	v_mov_b32_e32 v57, v35
	v_or_b32_e32 v56, 0x800, v34
	v_mul_f32_e32 v22, v22, v64
	v_mul_f32_e32 v23, v23, v64
	v_mul_f32_e32 v24, v24, v64
	v_mul_f32_e32 v25, v25, v64
	v_lshl_add_u64 v[56:57], v[42:43], 0, v[56:57]
	v_mul_f32_e32 v10, v10, v60
	v_mul_f32_e32 v11, v11, v60
	v_mul_f32_e32 v12, v12, v60
	v_mul_f32_e32 v13, v13, v60
	v_mul_f32_e32 v18, v18, v64
	v_mul_f32_e32 v19, v19, v64
	v_mul_f32_e32 v20, v20, v64
	v_mul_f32_e32 v21, v21, v64
	v_mul_f32_e32 v2, v2, v60
	v_mul_f32_e32 v3, v3, v60
	v_cmp_lt_i32_e32 vcc, s31, v1
	v_mul_f32_e32 v4, v4, v60
	v_mul_f32_e32 v5, v5, v60
	s_or_b64 s[14:15], vcc, s[14:15]
	v_mul_f32_e32 v6, v6, v64
	v_mul_f32_e32 v7, v7, v64
	v_mul_f32_e32 v8, v8, v64
	v_mul_f32_e32 v9, v9, v64
	s_waitcnt vmcnt(10)
	v_add_f32_e32 v104, 1.0, v104
	v_add_f32_e32 v105, 1.0, v105
	v_add_f32_e32 v106, 1.0, v106
	v_add_f32_e32 v107, 1.0, v107
	s_waitcnt vmcnt(9)
	v_mul_f32_e32 v104, v108, v104
	v_mul_f32_e32 v105, v109, v105
	v_mul_f32_e32 v106, v110, v106
	v_mul_f32_e32 v107, v111, v107
	s_waitcnt vmcnt(8)
	v_fma_f32 v14, v14, v104, v112
	v_fma_f32 v15, v15, v105, v113
	v_fma_f32 v16, v16, v106, v114
	v_fma_f32 v17, v17, v107, v115
	v_cvt_pk_bf16_f32 v14, v14, v15
	v_cvt_pk_bf16_f32 v15, v16, v17
	v_fma_f32 v22, v22, v104, v112
	v_fma_f32 v23, v23, v105, v113
	v_fma_f32 v24, v24, v106, v114
	v_fmac_f32_e32 v115, v25, v107
	v_cvt_pk_bf16_f32 v16, v22, v23
	v_cvt_pk_bf16_f32 v17, v24, v115
	global_store_dwordx2 v[38:39], v[14:15], off offset:512
	global_store_dwordx2 v[38:39], v[16:17], off offset:2560
	s_nop 0
	s_waitcnt vmcnt(9)
	v_add_f32_e32 v116, 1.0, v116
	v_add_f32_e32 v117, 1.0, v117
	v_add_f32_e32 v118, 1.0, v118
	v_add_f32_e32 v119, 1.0, v119
	s_waitcnt vmcnt(8)
	v_mul_f32_e32 v116, v120, v116
	v_mul_f32_e32 v117, v121, v117
	v_mul_f32_e32 v118, v122, v118
	v_mul_f32_e32 v119, v123, v119
	s_waitcnt vmcnt(7)
	v_fma_f32 v10, v10, v116, v124
	v_fma_f32 v11, v11, v117, v125
	v_fma_f32 v12, v12, v118, v126
	v_fma_f32 v13, v13, v119, v127
	v_cvt_pk_bf16_f32 v10, v10, v11
	v_cvt_pk_bf16_f32 v11, v12, v13
	v_fma_f32 v116, v18, v116, v124
	v_fma_f32 v117, v19, v117, v125
	v_fma_f32 v118, v20, v118, v126
	v_fmac_f32_e32 v127, v21, v119
	v_cvt_pk_bf16_f32 v12, v116, v117
	v_cvt_pk_bf16_f32 v13, v118, v127
	global_store_dwordx2 v[38:39], v[10:11], off offset:1024
	global_store_dwordx2 v[38:39], v[12:13], off offset:3072
	v_or_b32_e32 v34, 0xc00, v34
	v_lshl_add_u64 v[22:23], v[42:43], 0, v[34:35]
	s_waitcnt vmcnt(7)
	v_add_f32_e32 v136, 1.0, v136
	v_add_f32_e32 v137, 1.0, v137
	v_add_f32_e32 v138, 1.0, v138
	v_add_f32_e32 v139, 1.0, v139
	v_mul_f32_e32 v128, v128, v136
	v_mul_f32_e32 v129, v129, v137
	v_mul_f32_e32 v130, v130, v138
	v_mul_f32_e32 v131, v131, v139
	s_waitcnt vmcnt(6)
	v_fma_f32 v2, v2, v128, v140
	v_fma_f32 v3, v3, v129, v141
	v_fma_f32 v4, v4, v130, v142
	v_fma_f32 v5, v5, v131, v143
	v_cvt_pk_bf16_f32 v2, v2, v3
	v_cvt_pk_bf16_f32 v3, v4, v5
	v_fma_f32 v6, v6, v128, v140
	v_fma_f32 v7, v7, v129, v141
	v_fma_f32 v8, v8, v130, v142
	v_fmac_f32_e32 v143, v9, v131
	v_cvt_pk_bf16_f32 v4, v6, v7
	v_cvt_pk_bf16_f32 v5, v8, v143
	global_store_dwordx2 v[38:39], v[2:3], off offset:1536
	global_store_dwordx2 v[38:39], v[4:5], off offset:3584
	s_andn2_b64 exec, exec, s[14:15]
	s_cbranch_execz .LBB0_223

.LBB0_281:
	s_mov_b32 s98, 0
	v_mov_b32_e32 v255, 0x0
	v_bfe_u32 v1, v0, 0, 1
	v_lshlrev_b32_e32 v1, 7, v1
	v_xor_b32_e32 v255, v255, v1
	v_bfe_u32 v1, v0, 1, 3
	v_mul_u32_u24_e32 v1, 0x110, v1
	v_xor_b32_e32 v255, v255, v1
	v_bfe_u32 v1, v0, 4, 2
	v_lshlrev_b32_e32 v1, 4, v1
	v_xor_b32_e32 v255, v255, v1
	v_bfe_u32 v1, v0, 8, 1
	v_lshlrev_b32_e32 v1, 14, v1
	v_xor_b32_e32 v255, v255, v1
	v_add_u32_e32 v254, 0x10000, v255
	v_xor_b32_e32 v253, 0x880, v255
	v_xor_b32_e32 v252, 0x10880, v255
	v_mov_b32_e32 v251, 0x8000
	v_bfe_u32 v1, v0, 1, 3
	v_lshlrev_b32_e32 v1, 8, v1
	v_add_u32_e32 v251, v251, v1
	v_bfe_u32 v1, v0, 6, 2
	v_mul_u32_u24_e32 v1, 0x1800, v1
	v_add_u32_e32 v251, v251, v1
	v_mov_b32_e32 v2, 0x0
	v_bfe_u32 v1, v0, 0, 1
	v_lshlrev_b32_e32 v1, 7, v1
	v_xor_b32_e32 v2, v2, v1
	v_bfe_u32 v1, v0, 1, 3
	v_lshlrev_b32_e32 v1, 4, v1
	v_xor_b32_e32 v2, v2, v1
	v_bfe_u32 v1, v0, 4, 2
	v_lshlrev_b32_e32 v1, 4, v1
	v_xor_b32_e32 v2, v2, v1
	v_bfe_u32 v1, v0, 6, 1
	v_lshlrev_b32_e32 v1, 7, v1
	v_xor_b32_e32 v2, v2, v1
	v_add_u32_e32 v251, v251, v2
	v_add_u32_e32 v250, 0x10000, v251
	v_mov_b32_e32 v249, 0x8800
	v_bfe_u32 v1, v0, 1, 3
	v_lshlrev_b32_e32 v1, 8, v1
	v_add_u32_e32 v249, v249, v1
	v_bfe_u32 v1, v0, 6, 2
	v_mul_u32_u24_e32 v1, 0x1800, v1
	v_add_u32_e32 v249, v249, v1
	v_mov_b32_e32 v2, 0x80
	v_bfe_u32 v1, v0, 0, 1
	v_lshlrev_b32_e32 v1, 7, v1
	v_xor_b32_e32 v2, v2, v1
	v_bfe_u32 v1, v0, 1, 3
	v_lshlrev_b32_e32 v1, 4, v1
	v_xor_b32_e32 v2, v2, v1
	v_bfe_u32 v1, v0, 4, 2
	v_lshlrev_b32_e32 v1, 4, v1
	v_xor_b32_e32 v2, v2, v1
	v_bfe_u32 v1, v0, 6, 1
	v_lshlrev_b32_e32 v1, 7, v1
	v_xor_b32_e32 v2, v2, v1
	v_add_u32_e32 v249, v249, v2
	v_add_u32_e32 v248, 0x10000, v249
	v_xor_b32_e32 v247, 0x40, v255
	v_xor_b32_e32 v246, 0x10040, v255
	v_xor_b32_e32 v245, 0x8c0, v255
	v_xor_b32_e32 v244, 0x108c0, v255
	v_xor_b32_e32 v243, 0x40, v251
	v_xor_b32_e32 v242, 0x10040, v251
	v_xor_b32_e32 v241, 0x40, v249
	v_xor_b32_e32 v240, 0x10040, v249
	v_mov_b32_e32 v239, 0x0
	v_bfe_u32 v1, v0, 0, 4
	v_lshlrev_b32_e32 v1, 4, v1
	v_xor_b32_e32 v239, v239, v1
	v_bfe_u32 v1, v0, 4, 4
	v_mul_u32_u24_e32 v1, 0x110, v1
	v_xor_b32_e32 v239, v239, v1
	v_bfe_u32 v1, v0, 8, 1
	v_lshlrev_b32_e32 v1, 12, v1
	v_xor_b32_e32 v239, v239, v1
	v_add_u32_e32 v238, 0x10000, v239
	v_mov_b32_e32 v237, 0x0
	v_bfe_u32 v1, v0, 0, 3
	v_lshlrev_b32_e32 v1, 4, v1
	v_add_u32_e32 v237, v237, v1
	v_bfe_u32 v1, v0, 3, 6
	v_lshlrev_b32_e32 v1, 11, v1
	v_add_u32_e32 v237, v237, v1
	v_add_u32_e32 v236, 0x20000, v237
	v_add_u32_e32 v235, 0x40000, v237
	v_add_u32_e32 v234, 0x60000, v237
	v_mov_b32_e32 v1, v0
	s_load_dword s2, s[0:1], 0xe0
	s_mov_b32 s3, s10
	v_mov_b32_e32 v1, v0
	s_waitcnt lgkmcnt(0)
	s_lshr_b32 s11, s2, 3
	v_cvt_f32_u32_e32 v2, s11
	s_mov_b32 s2, s10
	s_ashr_i32 s3, s2, 3
	v_rcp_iflag_f32_e32 v2, v2
	s_ashr_i32 s4, s2, 31
	s_sub_i32 s2, 0, s11
	s_abs_i32 s3, s3
	v_mul_f32_e32 v1, 0x4f7ffffe, v2
	v_cvt_u32_f32_e32 v1, v1
	s_mov_b32 s45, 0
	v_readfirstlane_b32 s5, v1
	s_mul_i32 s2, s2, s5
	s_mul_hi_u32 s2, s5, s2
	s_add_i32 s2, s5, s2
	s_mul_hi_u32 s5, s3, s2
	s_mul_i32 s5, s5, s11
	s_sub_i32 s3, s3, s5
	s_sub_i32 s5, s3, s11
	s_cmp_ge_u32 s3, s11
	s_cselect_b32 s3, s5, s3
	s_sub_i32 s5, s3, s11
	s_cmp_ge_u32 s3, s11
	s_cselect_b32 s3, s5, s3
	s_xor_b32 s3, s3, s4
	s_sub_i32 s24, s3, s4
	s_mov_b32 s3, s10
	s_cmpk_gt_i32 s24, 0x5f
	s_cbranch_scc1 .LBB0_361
	s_load_dwordx2 s[4:5], s[16:17], 0xd0
	s_mov_b32 s3, s10
	v_mov_b32_e32 v54, 0
	v_mov_b32_e32 v1, v0
	s_waitcnt lgkmcnt(0)
	s_add_u32 s25, s4, 0x17f0000
	s_addc_u32 s26, s5, 0
	s_add_u32 s8, s4, 0x37f0000
	s_addc_u32 s9, s5, 0
	s_add_u32 s27, s4, 0x50000
	s_addc_u32 s28, s5, 0
	s_ashr_i32 s4, s24, 31
	s_lshr_b32 s4, s4, 27
	s_add_i32 s4, s24, s4
	s_ashr_i32 s4, s4, 5
	s_lshl_b32 s5, s24, 1
	s_lshl_b32 s12, s4, 6
	s_sub_i32 s5, s5, s12
	s_lshl_b32 s4, s4, 2
	s_and_b32 s12, s24, 3
	s_or_b32 s29, s4, s12
	s_sub_i32 s4, s11, s24
	s_addk_i32 s4, 0x5f
	s_mul_hi_u32 s2, s4, s2
	s_mul_i32 s12, s2, s11
	s_sub_i32 s4, s4, s12
	s_add_i32 s12, s2, 1
	s_sub_i32 s13, s4, s11
	s_cmp_ge_u32 s4, s11
	s_cselect_b32 s2, s12, s2
	s_cselect_b32 s4, s13, s4
	s_add_i32 s12, s2, 1
	s_cmp_ge_u32 s4, s11
	s_cselect_b32 s2, s12, s2
	s_and_b32 s3, s3, 7
	s_and_b32 s4, s5, -8
	s_lshl_b32 s30, s2, 4
	s_mul_i32 s2, s29, 0xc0
	s_or_b32 s31, s3, s4
	s_ashr_i32 s3, s2, 31
	s_lshl_b64 s[2:3], s[2:3], 11
	v_lshlrev_b32_e32 v2, 8, v1
	v_lshlrev_b32_e32 v1, 4, v1
	s_add_u32 s2, s27, s2
	v_and_b32_e32 v1, 0x70, v1
	s_movk_i32 s33, 0xf800
	v_mov_b32_e32 v175, 0
	s_addc_u32 s3, s28, s3
	v_and_or_b32 v174, v2, s33, v1
	s_lshl_b32 s4, s31, 8
	v_lshl_add_u64 v[2:3], s[2:3], 0, v[174:175]
	s_mov_b32 s12, 0x40000
	s_ashr_i32 s5, s4, 31
	v_add_co_u32_e32 v14, vcc, s12, v2
	s_lshl_b64 s[4:5], s[4:5], 11
	s_nop 0
	v_addc_co_u32_e32 v15, vcc, 0, v3, vcc
	s_mov_b32 s34, 0x20000
	s_add_u32 s4, s25, s4
	v_add_co_u32_e32 v16, vcc, s34, v2
	s_addc_u32 s5, s26, s5
	s_nop 0
	v_addc_co_u32_e32 v17, vcc, 0, v3, vcc
	global_load_dwordx4 v[2:5], v[14:15], off
	global_load_dwordx4 v[6:9], v[16:17], off
	global_load_dwordx4 v[10:13], v174, s[2:3]
	v_lshl_add_u64 v[14:15], s[4:5], 0, v[174:175]
	s_mov_b32 s13, 0x60000
	v_add_co_u32_e32 v30, vcc, s13, v14
	v_mov_b32_e32 v1, v0
	s_nop 0
	v_addc_co_u32_e32 v31, vcc, 0, v15, vcc
	v_add_co_u32_e32 v32, vcc, s12, v14
	s_movk_i32 s36, 0xf0
	s_nop 0
	v_addc_co_u32_e32 v33, vcc, 0, v15, vcc
	v_add_co_u32_e32 v34, vcc, s34, v14
	s_mov_b32 s35, 2
	s_nop 0
	v_addc_co_u32_e32 v35, vcc, 0, v15, vcc
	global_load_dwordx4 v[14:17], v174, s[4:5]
	global_load_dwordx4 v[18:21], v[34:35], off
	global_load_dwordx4 v[22:25], v[32:33], off
	global_load_dwordx4 v[26:29], v[30:31], off
	v_mov_b32_e32 v30, v0
	v_ashrrev_i32_e32 v31, 4, v1
	v_xor_b32_e32 v1, v31, v1
	v_lshlrev_b32_e32 v31, 8, v31
	v_lshlrev_b32_e32 v1, 4, v1
	v_and_or_b32 v1, v1, s36, v31
	s_movk_i32 s37, 0xff80
	s_mov_b32 s38, 0x10000
	s_mov_b32 s39, 0x18000
	s_movk_i32 s40, 0x8a0
	s_movk_i32 s41, 0x1140
	v_mov_b32_e32 v176, 0x18000
	s_mov_b32 s22, 2
	s_mov_b32 s42, s24
	s_mov_b32 s43, s29
	s_mov_b32 s44, s31
	v_mov_b32_e32 v55, v54
	v_mov_b32_e32 v56, v54
	v_mov_b32_e32 v57, v54
	v_mov_b32_e32 v82, v54
	v_mov_b32_e32 v83, v54
	v_mov_b32_e32 v84, v54
	v_mov_b32_e32 v85, v54
	v_mov_b32_e32 v86, v54
	v_mov_b32_e32 v87, v54
	v_mov_b32_e32 v88, v54
	v_mov_b32_e32 v89, v54
	v_mov_b32_e32 v90, v54
	v_mov_b32_e32 v91, v54
	v_mov_b32_e32 v92, v54
	v_mov_b32_e32 v93, v54
	v_mov_b32_e32 v94, v54
	v_mov_b32_e32 v95, v54
	v_mov_b32_e32 v96, v54
	v_mov_b32_e32 v97, v54
	s_waitcnt vmcnt(4)
	ds_write_b128 v1, v[10:13] offset:32768
	ds_write_b128 v1, v[6:9] offset:40960
	ds_write_b128 v1, v[2:5] offset:49152
	s_waitcnt vmcnt(3)
	ds_write_b128 v1, v[14:17]
	s_waitcnt vmcnt(2)
	ds_write_b128 v1, v[18:21] offset:8192
	s_waitcnt vmcnt(1)
	ds_write_b128 v1, v[22:25] offset:16384
	s_waitcnt vmcnt(0)
	ds_write_b128 v1, v[26:29] offset:24576
	v_mov_b32_e32 v98, v54
	v_lshlrev_b32_e32 v2, 4, v30
	v_lshlrev_b32_e32 v1, 8, v30
	v_and_b32_e32 v2, 0x70, v2
	v_and_or_b32 v174, v1, s33, v2
	v_lshl_add_u64 v[2:3], s[2:3], 0, v[174:175]
	v_add_co_u32_e32 v10, vcc, s12, v2
	v_mov_b32_e32 v1, 0x10000
	s_nop 0
	v_addc_co_u32_e32 v11, vcc, 0, v3, vcc
	v_add_co_u32_e32 v12, vcc, s34, v2
	v_mov_b32_e32 v99, v54
	s_nop 0
	v_addc_co_u32_e32 v13, vcc, 0, v3, vcc
	global_load_dwordx4 v[2:5], v[10:11], off offset:128
	global_load_dwordx4 v[6:9], v[12:13], off offset:128
	v_lshl_add_u64 v[10:11], s[4:5], 0, v[174:175]
	v_add_co_u32_e32 v12, vcc, s13, v10
	v_mov_b32_e32 v100, v54
	s_nop 0
	v_addc_co_u32_e32 v13, vcc, 0, v11, vcc
	v_add_co_u32_e32 v22, vcc, s12, v10
	v_mov_b32_e32 v101, v54
	s_nop 0
	v_addc_co_u32_e32 v23, vcc, 0, v11, vcc
	v_add_co_u32_e32 v30, vcc, s34, v10
	global_load_dwordx4 v[14:17], v[12:13], off offset:128
	global_load_dwordx4 v[18:21], v[22:23], off offset:128
	v_addc_co_u32_e32 v31, vcc, 0, v11, vcc
	global_load_dwordx4 v[10:13], v174, s[2:3] offset:128
	global_load_dwordx4 v[22:25], v[30:31], off offset:128
	global_load_dwordx4 v[26:29], v174, s[4:5] offset:128
	v_mov_b32_e32 v102, v54
	v_mov_b32_e32 v103, v54
	v_mov_b32_e32 v104, v54
	v_mov_b32_e32 v105, v54
	v_mov_b32_e32 v106, v54
	v_mov_b32_e32 v107, v54
	v_mov_b32_e32 v108, v54
	v_mov_b32_e32 v109, v54
	v_mov_b32_e32 v110, v54
	v_mov_b32_e32 v111, v54
	v_mov_b32_e32 v112, v54
	v_mov_b32_e32 v113, v54
	v_mov_b32_e32 v114, v54
	v_mov_b32_e32 v115, v54
	v_mov_b32_e32 v116, v54
	v_mov_b32_e32 v117, v54
	v_mov_b32_e32 v118, v54
	v_mov_b32_e32 v119, v54
	v_mov_b32_e32 v120, v54
	v_mov_b32_e32 v121, v54
	v_mov_b32_e32 v122, v54
	v_mov_b32_e32 v123, v54
	v_mov_b32_e32 v124, v54
	v_mov_b32_e32 v125, v54
	v_mov_b32_e32 v78, v54
	v_mov_b32_e32 v79, v54
	v_mov_b32_e32 v80, v54
	v_mov_b32_e32 v81, v54
	v_mov_b32_e32 v74, v54
	v_mov_b32_e32 v75, v54
	v_mov_b32_e32 v76, v54
	v_mov_b32_e32 v77, v54
	v_mov_b32_e32 v70, v54
	v_mov_b32_e32 v71, v54
	v_mov_b32_e32 v72, v54
	v_mov_b32_e32 v73, v54
	v_mov_b32_e32 v66, v54
	v_mov_b32_e32 v67, v54
	v_mov_b32_e32 v68, v54
	v_mov_b32_e32 v69, v54
	v_mov_b32_e32 v62, v54
	v_mov_b32_e32 v63, v54
	v_mov_b32_e32 v64, v54
	v_mov_b32_e32 v65, v54
	v_mov_b32_e32 v58, v54
	v_mov_b32_e32 v59, v54
	v_mov_b32_e32 v60, v54
	v_mov_b32_e32 v61, v54
	v_mov_b32_e32 v50, v54
	v_mov_b32_e32 v51, v54
	v_mov_b32_e32 v52, v54
	v_mov_b32_e32 v53, v54
	v_mov_b32_e32 v46, v54
	v_mov_b32_e32 v47, v54
	v_mov_b32_e32 v48, v54
	v_mov_b32_e32 v49, v54
	v_mov_b32_e32 v42, v54
	v_mov_b32_e32 v43, v54
	v_mov_b32_e32 v44, v54
	v_mov_b32_e32 v45, v54
	v_mov_b32_e32 v38, v54
	v_mov_b32_e32 v39, v54
	v_mov_b32_e32 v40, v54
	v_mov_b32_e32 v41, v54
	v_mov_b32_e32 v34, v54
	v_mov_b32_e32 v35, v54
	v_mov_b32_e32 v36, v54
	v_mov_b32_e32 v37, v54
	v_mov_b32_e32 v30, v54
	v_mov_b32_e32 v31, v54
	v_mov_b32_e32 v32, v54
	v_mov_b32_e32 v33, v54
	s_waitcnt lgkmcnt(0)
	s_barrier
	s_waitcnt vmcnt(0)
	s_branch .LBB0_285

.LBB0_956:
	s_mov_b32 s98, 0
	v_mov_b32_e32 v255, 0x0
	v_bfe_u32 v1, v0, 0, 1
	v_lshlrev_b32_e32 v1, 7, v1
	v_xor_b32_e32 v255, v255, v1
	v_bfe_u32 v1, v0, 1, 3
	v_mul_u32_u24_e32 v1, 0x110, v1
	v_xor_b32_e32 v255, v255, v1
	v_bfe_u32 v1, v0, 4, 2
	v_lshlrev_b32_e32 v1, 4, v1
	v_xor_b32_e32 v255, v255, v1
	v_bfe_u32 v1, v0, 8, 1
	v_lshlrev_b32_e32 v1, 14, v1
	v_xor_b32_e32 v255, v255, v1
	v_add_u32_e32 v254, 0x10000, v255
	v_xor_b32_e32 v253, 0x880, v255
	v_xor_b32_e32 v252, 0x10880, v255
	v_mov_b32_e32 v251, 0x8000
	v_bfe_u32 v1, v0, 0, 1
	v_lshlrev_b32_e32 v1, 7, v1
	v_xor_b32_e32 v251, v251, v1
	v_bfe_u32 v1, v0, 1, 3
	v_mul_u32_u24_e32 v1, 0x110, v1
	v_xor_b32_e32 v251, v251, v1
	v_bfe_u32 v1, v0, 4, 2
	v_lshlrev_b32_e32 v1, 4, v1
	v_xor_b32_e32 v251, v251, v1
	v_bfe_u32 v1, v0, 6, 2
	v_lshlrev_b32_e32 v1, 13, v1
	v_xor_b32_e32 v251, v251, v1
	v_add_u32_e32 v250, 0x10000, v251
	v_xor_b32_e32 v249, 0x880, v251
	v_xor_b32_e32 v248, 0x10880, v251
	v_xor_b32_e32 v247, 0x40, v255
	v_xor_b32_e32 v246, 0x10040, v255
	v_xor_b32_e32 v245, 0x8c0, v255
	v_xor_b32_e32 v244, 0x108c0, v255
	v_xor_b32_e32 v243, 0x40, v251
	v_xor_b32_e32 v242, 0x10040, v251
	v_xor_b32_e32 v241, 0x8c0, v251
	v_xor_b32_e32 v237, 0x108c0, v251
	v_mov_b32_e32 v236, 0x0
	v_bfe_u32 v1, v0, 0, 4
	v_lshlrev_b32_e32 v1, 4, v1
	v_xor_b32_e32 v236, v236, v1
	v_bfe_u32 v1, v0, 4, 4
	v_mul_u32_u24_e32 v1, 0x110, v1
	v_xor_b32_e32 v236, v236, v1
	v_bfe_u32 v1, v0, 8, 1
	v_lshlrev_b32_e32 v1, 12, v1
	v_xor_b32_e32 v236, v236, v1
	v_add_u32_e32 v235, 0x10000, v236
	v_mov_b32_e32 v234, 0x0
	v_bfe_u32 v1, v0, 0, 3
	v_lshlrev_b32_e32 v1, 4, v1
	v_add_u32_e32 v234, v234, v1
	v_bfe_u32 v1, v0, 3, 6
	v_lshlrev_b32_e32 v1, 11, v1
	v_add_u32_e32 v234, v234, v1
	v_add_u32_e32 v233, 0x20000, v234
	v_add_u32_e32 v232, 0x40000, v234
	v_add_u32_e32 v231, 0x60000, v234
	v_mov_b32_e32 v1, v0
	s_load_dword s2, s[0:1], 0xe0
	s_mov_b32 s3, s10
	v_mov_b32_e32 v1, v0
	s_waitcnt lgkmcnt(0)
	s_lshr_b32 s11, s2, 3
	s_waitcnt vmcnt(0)
	v_cvt_f32_u32_e32 v2, s11
	s_mov_b32 s2, s10
	s_ashr_i32 s3, s2, 3
	v_rcp_iflag_f32_e32 v2, v2
	s_ashr_i32 s4, s2, 31
	s_sub_i32 s2, 0, s11
	s_abs_i32 s3, s3
	v_mul_f32_e32 v1, 0x4f7ffffe, v2
	v_cvt_u32_f32_e32 v1, v1
	s_mov_b32 s52, 0
	v_readfirstlane_b32 s5, v1
	s_mul_i32 s2, s2, s5
	s_mul_hi_u32 s2, s5, s2
	s_add_i32 s2, s5, s2
	s_mul_hi_u32 s5, s3, s2
	s_mul_i32 s5, s5, s11
	s_sub_i32 s3, s3, s5
	s_sub_i32 s5, s3, s11
	s_cmp_ge_u32 s3, s11
	s_cselect_b32 s3, s5, s3
	s_sub_i32 s5, s3, s11
	s_cmp_ge_u32 s3, s11
	s_cselect_b32 s3, s5, s3
	s_xor_b32 s3, s3, s4
	s_sub_i32 s30, s3, s4
	s_mov_b32 s3, s10
	s_cmp_gt_i32 s30, 31
	s_cbranch_scc1 .LBB0_1020
	s_load_dwordx4 s[4:7], s[16:17], 0xc8
	s_load_dwordx4 s[12:15], s[16:17], 0x0
	s_mov_b32 s3, s10
	v_mov_b32_e32 v82, 0
	s_waitcnt lgkmcnt(0)
	s_add_u32 s31, s6, 0x17f0000
	s_addc_u32 s33, s7, 0
	s_add_u32 s20, s6, 0x6000
	s_addc_u32 s21, s7, 0
	s_add_u32 s34, s6, 0x570000
	s_addc_u32 s35, s7, 0
	s_ashr_i32 s6, s30, 31
	s_lshr_b32 s6, s6, 27
	s_add_i32 s6, s30, s6
	s_ashr_i32 s6, s6, 5
	s_lshl_b32 s7, s6, 6
	s_lshl_b32 s22, s30, 1
	s_sub_i32 s7, s22, s7
	s_lshl_b32 s6, s6, 2
	s_and_b32 s22, s30, 3
	s_or_b32 s36, s6, s22
	s_sub_i32 s6, s11, s30
	s_add_i32 s6, s6, 31
	s_mul_hi_u32 s2, s6, s2
	s_mul_i32 s22, s2, s11
	s_sub_i32 s6, s6, s22
	s_add_i32 s22, s2, 1
	s_sub_i32 s23, s6, s11
	s_cmp_ge_u32 s6, s11
	s_cselect_b32 s2, s22, s2
	s_cselect_b32 s6, s23, s6
	s_add_i32 s22, s2, 1
	s_cmp_ge_u32 s6, s11
	s_cselect_b32 s2, s22, s2
	s_and_b32 s3, s3, 7
	s_and_b32 s6, s7, -8
	s_lshl_b32 s37, s2, 4
	v_mov_b32_e32 v1, v0
	s_lshl_b32 s2, s36, 8
	s_or_b32 s38, s3, s6
	s_ashr_i32 s3, s2, 31
	s_lshl_b64 s[2:3], s[2:3], 11
	v_lshlrev_b32_e32 v2, 8, v1
	v_lshlrev_b32_e32 v1, 4, v1
	s_add_u32 s2, s34, s2
	v_and_b32_e32 v1, 0x70, v1
	s_movk_i32 s39, 0xf800
	v_mov_b32_e32 v239, 0
	s_addc_u32 s3, s35, s3
	v_and_or_b32 v238, v2, s39, v1
	v_lshl_add_u64 v[10:11], s[2:3], 0, v[238:239]
	s_mov_b32 s40, 0x60000
	v_add_co_u32_e32 v12, vcc, s40, v10
	s_lshl_b32 s6, s38, 8
	s_nop 0
	v_addc_co_u32_e32 v13, vcc, 0, v11, vcc
	s_mov_b32 s22, 0x40000
	s_ashr_i32 s7, s6, 31
	v_add_co_u32_e32 v14, vcc, s22, v10
	s_lshl_b64 s[6:7], s[6:7], 11
	s_nop 0
	v_addc_co_u32_e32 v15, vcc, 0, v11, vcc
	s_mov_b32 s41, 0x20000
	s_add_u32 s6, s31, s6
	v_add_co_u32_e32 v18, vcc, s41, v10
	s_addc_u32 s7, s33, s7
	s_nop 0
	v_addc_co_u32_e32 v19, vcc, 0, v11, vcc
	v_lshl_add_u64 v[30:31], s[6:7], 0, v[238:239]
	v_add_co_u32_e32 v32, vcc, s22, v30
	global_load_dwordx4 v[2:5], v[12:13], off
	global_load_dwordx4 v[6:9], v[14:15], off
	v_addc_co_u32_e32 v33, vcc, 0, v31, vcc
	v_add_co_u32_e32 v34, vcc, s41, v30
	global_load_dwordx4 v[10:13], v[18:19], off
	global_load_dwordx4 v[14:17], v238, s[2:3]
	v_addc_co_u32_e32 v35, vcc, 0, v31, vcc
	global_load_dwordx4 v[18:21], v[32:33], off
	global_load_dwordx4 v[22:25], v[34:35], off
	global_load_dwordx4 v[26:29], v238, s[6:7]
	v_add_co_u32_e32 v30, vcc, s40, v30
	v_mov_b32_e32 v1, v0
	s_nop 0
	v_addc_co_u32_e32 v31, vcc, 0, v31, vcc
	global_load_dwordx4 v[30:33], v[30:31], off
	s_movk_i32 s43, 0xf0
	v_ashrrev_i32_e32 v35, 4, v1
	v_xor_b32_e32 v1, v35, v1
	v_lshlrev_b32_e32 v35, 8, v35
	v_lshlrev_b32_e32 v1, 4, v1
	v_mov_b32_e32 v34, v0
	v_and_or_b32 v1, v1, s43, v35
	s_mov_b32 s42, 2
	s_movk_i32 s44, 0xff80
	s_mov_b32 s45, 0x10000
	s_mov_b32 s46, 0x11000
	s_movk_i32 s47, 0x1800
	s_movk_i32 s48, 0x1fff
	v_mov_b32_e32 v240, 0x8040
	s_mov_b32 s28, 2
	s_mov_b32 s49, s30
	s_mov_b32 s50, s36
	s_mov_b32 s51, s38
	v_mov_b32_e32 v83, v82
	v_mov_b32_e32 v84, v82
	v_mov_b32_e32 v85, v82
	v_mov_b32_e32 v102, v82
	v_mov_b32_e32 v103, v82
	v_mov_b32_e32 v104, v82
	v_mov_b32_e32 v105, v82
	v_mov_b32_e32 v106, v82
	v_mov_b32_e32 v107, v82
	v_mov_b32_e32 v108, v82
	v_mov_b32_e32 v109, v82
	v_mov_b32_e32 v110, v82
	s_waitcnt vmcnt(4)
	ds_write_b128 v1, v[14:17] offset:32768
	ds_write_b128 v1, v[10:13] offset:40960
	ds_write_b128 v1, v[6:9] offset:49152
	ds_write_b128 v1, v[2:5] offset:57344
	s_waitcnt vmcnt(1)
	ds_write_b128 v1, v[26:29]
	ds_write_b128 v1, v[22:25] offset:8192
	ds_write_b128 v1, v[18:21] offset:16384
	s_waitcnt vmcnt(0)
	ds_write_b128 v1, v[30:33] offset:24576
	v_mov_b32_e32 v111, v82
	v_lshlrev_b32_e32 v2, 4, v34
	v_lshlrev_b32_e32 v1, 8, v34
	v_and_b32_e32 v2, 0x70, v2
	v_and_or_b32 v238, v1, s39, v2
	v_lshl_add_u64 v[10:11], s[2:3], 0, v[238:239]
	v_add_co_u32_e32 v12, vcc, s40, v10
	v_lshl_add_u64 v[16:17], s[6:7], 0, v[238:239]
	s_nop 0
	v_addc_co_u32_e32 v13, vcc, 0, v11, vcc
	v_add_co_u32_e32 v14, vcc, s22, v10
	v_mov_b32_e32 v1, 0x10000
	s_nop 0
	v_addc_co_u32_e32 v15, vcc, 0, v11, vcc
	global_load_dwordx4 v[2:5], v[12:13], off offset:128
	global_load_dwordx4 v[6:9], v[14:15], off offset:128
	v_add_co_u32_e32 v14, vcc, s41, v10
	v_mov_b32_e32 v112, v82
	s_nop 0
	v_addc_co_u32_e32 v15, vcc, 0, v11, vcc
	v_add_co_u32_e32 v22, vcc, s40, v16
	v_mov_b32_e32 v113, v82
	s_nop 0
	v_addc_co_u32_e32 v23, vcc, 0, v17, vcc
	v_add_co_u32_e32 v34, vcc, s22, v16
	global_load_dwordx4 v[10:13], v[14:15], off offset:128
	global_load_dwordx4 v[18:21], v[22:23], off offset:128
	v_addc_co_u32_e32 v35, vcc, 0, v17, vcc
	v_add_co_u32_e32 v36, vcc, s41, v16
	v_mov_b32_e32 v114, v82
	s_nop 0
	v_addc_co_u32_e32 v37, vcc, 0, v17, vcc
	global_load_dwordx4 v[22:25], v[34:35], off offset:128
	global_load_dwordx4 v[26:29], v[36:37], off offset:128
	global_load_dwordx4 v[14:17], v238, s[2:3] offset:128
	global_load_dwordx4 v[30:33], v238, s[6:7] offset:128
	v_mov_b32_e32 v115, v82
	v_mov_b32_e32 v116, v82
	v_mov_b32_e32 v117, v82
	v_mov_b32_e32 v118, v82
	v_mov_b32_e32 v119, v82
	v_mov_b32_e32 v120, v82
	v_mov_b32_e32 v121, v82
	v_mov_b32_e32 v122, v82
	v_mov_b32_e32 v123, v82
	v_mov_b32_e32 v124, v82
	v_mov_b32_e32 v125, v82
	v_mov_b32_e32 v126, v82
	v_mov_b32_e32 v127, v82
	v_mov_b32_e32 v128, v82
	v_mov_b32_e32 v129, v82
	v_mov_b32_e32 v130, v82
	v_mov_b32_e32 v131, v82
	v_mov_b32_e32 v132, v82
	v_mov_b32_e32 v133, v82
	v_mov_b32_e32 v134, v82
	v_mov_b32_e32 v135, v82
	v_mov_b32_e32 v136, v82
	v_mov_b32_e32 v137, v82
	v_mov_b32_e32 v138, v82
	v_mov_b32_e32 v139, v82
	v_mov_b32_e32 v140, v82
	v_mov_b32_e32 v141, v82
	v_mov_b32_e32 v142, v82
	v_mov_b32_e32 v143, v82
	v_mov_b32_e32 v144, v82
	v_mov_b32_e32 v145, v82
	v_mov_b32_e32 v146, v82
	v_mov_b32_e32 v147, v82
	v_mov_b32_e32 v148, v82
	v_mov_b32_e32 v149, v82
	v_mov_b32_e32 v150, v82
	v_mov_b32_e32 v151, v82
	v_mov_b32_e32 v152, v82
	v_mov_b32_e32 v153, v82
	v_mov_b32_e32 v154, v82
	v_mov_b32_e32 v155, v82
	v_mov_b32_e32 v156, v82
	v_mov_b32_e32 v157, v82
	v_mov_b32_e32 v158, v82
	v_mov_b32_e32 v159, v82
	v_mov_b32_e32 v160, v82
	v_mov_b32_e32 v161, v82
	v_mov_b32_e32 v98, v82
	v_mov_b32_e32 v99, v82
	v_mov_b32_e32 v100, v82
	v_mov_b32_e32 v101, v82
	v_mov_b32_e32 v94, v82
	v_mov_b32_e32 v95, v82
	v_mov_b32_e32 v96, v82
	v_mov_b32_e32 v97, v82
	v_mov_b32_e32 v90, v82
	v_mov_b32_e32 v91, v82
	v_mov_b32_e32 v92, v82
	v_mov_b32_e32 v93, v82
	v_mov_b32_e32 v86, v82
	v_mov_b32_e32 v87, v82
	v_mov_b32_e32 v88, v82
	v_mov_b32_e32 v89, v82
	v_mov_b32_e32 v78, v82
	v_mov_b32_e32 v79, v82
	v_mov_b32_e32 v80, v82
	v_mov_b32_e32 v81, v82
	v_mov_b32_e32 v74, v82
	v_mov_b32_e32 v75, v82
	v_mov_b32_e32 v76, v82
	v_mov_b32_e32 v77, v82
	v_mov_b32_e32 v70, v82
	v_mov_b32_e32 v71, v82
	v_mov_b32_e32 v72, v82
	v_mov_b32_e32 v73, v82
	v_mov_b32_e32 v66, v82
	v_mov_b32_e32 v67, v82
	v_mov_b32_e32 v68, v82
	v_mov_b32_e32 v69, v82
	v_mov_b32_e32 v62, v82
	v_mov_b32_e32 v63, v82
	v_mov_b32_e32 v64, v82
	v_mov_b32_e32 v65, v82
	v_mov_b32_e32 v58, v82
	v_mov_b32_e32 v59, v82
	v_mov_b32_e32 v60, v82
	v_mov_b32_e32 v61, v82
	v_mov_b32_e32 v54, v82
	v_mov_b32_e32 v55, v82
	v_mov_b32_e32 v56, v82
	v_mov_b32_e32 v57, v82
	v_mov_b32_e32 v50, v82
	v_mov_b32_e32 v51, v82
	v_mov_b32_e32 v52, v82
	v_mov_b32_e32 v53, v82
	v_mov_b32_e32 v46, v82
	v_mov_b32_e32 v47, v82
	v_mov_b32_e32 v48, v82
	v_mov_b32_e32 v49, v82
	v_mov_b32_e32 v42, v82
	v_mov_b32_e32 v43, v82
	v_mov_b32_e32 v44, v82
	v_mov_b32_e32 v45, v82
	v_mov_b32_e32 v38, v82
	v_mov_b32_e32 v39, v82
	v_mov_b32_e32 v40, v82
	v_mov_b32_e32 v41, v82
	v_mov_b32_e32 v34, v82
	v_mov_b32_e32 v35, v82
	v_mov_b32_e32 v36, v82
	v_mov_b32_e32 v37, v82
	s_waitcnt lgkmcnt(0)
	s_barrier
	s_waitcnt vmcnt(0)
	s_branch .LBB0_960

.LBB0_1079:
	v_cmp_lt_i32_e32 vcc, v22, v21
	v_mov_b32_e32 v2, v0
	v_add_u32_e32 v4, 0xffffe000, v13
	v_cndmask_b32_e32 v5, v20, v22, vcc
	v_cmp_lt_i32_e32 vcc, v23, v21
	v_ashrrev_i32_e32 v4, 11, v4
	v_lshlrev_b32_e32 v100, 2, v5
	v_cndmask_b32_e32 v6, v20, v23, vcc
	v_cmp_lt_i32_e32 vcc, v24, v21
	v_lshrrev_b32_e32 v5, 5, v2
	v_lshlrev_b32_e32 v101, 2, v6
	v_cndmask_b32_e32 v8, v20, v24, vcc
	v_cmp_lt_i32_e32 vcc, v25, v21
	v_mad_i32_i24 v6, v4, s30, s30
	v_and_b32_e32 v4, 6, v5
	v_cndmask_b32_e32 v9, v20, v25, vcc
	v_cmp_lt_i32_e32 vcc, v26, v21
	s_load_dwordx2 s[28:29], s[16:17], 0x50
	v_add_u32_e32 v4, v13, v4
	v_cndmask_b32_e32 v10, v20, v26, vcc
	v_cmp_lt_i32_e32 vcc, v27, v21
	v_lshlrev_b32_e32 v2, 2, v2
	v_ashrrev_i32_e32 v5, 31, v4
	v_cndmask_b32_e32 v14, v20, v27, vcc
	v_lshlrev_b32_e32 v105, 2, v14
	v_and_b32_e32 v2, 0xfc, v2
	v_cmp_lt_i32_e32 vcc, s31, v4
	v_lshlrev_b64 v[14:15], 12, v[4:5]
	v_lshlrev_b32_e32 v102, 2, v8
	v_lshlrev_b32_e32 v104, 2, v10
	v_lshlrev_b32_e32 v10, 2, v2
	v_cndmask_b32_e32 v8, 0, v6, vcc
	v_lshlrev_b64 v[4:5], 11, v[4:5]
	v_lshl_add_u64 v[14:15], s[4:5], 0, v[14:15]
	v_mov_b32_e32 v3, v11
	v_lshlrev_b32_e32 v103, 2, v9
	v_lshlrev_b32_e32 v2, 1, v2
	v_ashrrev_i32_e32 v9, 31, v8
	v_lshl_add_u64 v[4:5], s[6:7], 0, v[4:5]
	v_lshl_add_u64 v[44:45], v[14:15], 0, v[10:11]
	s_waitcnt lgkmcnt(0)
	global_load_dwordx4 v[28:31], v10, s[28:29]
	v_lshl_add_u64 v[8:9], v[8:9], 2, s[20:21]
	v_lshl_add_u64 v[14:15], v[4:5], 0, v[2:3]
	global_load_dwordx4 v[32:35], v[44:45], off
	global_load_dwordx4 v[36:39], v[44:45], off offset:1024
	global_load_dwordx4 v[40:43], v[44:45], off offset:2048
	global_load_dwordx4 v[2:5], v[44:45], off offset:3072
	v_add_co_u32_e32 v64, vcc, s33, v44
	v_mov_b32_e32 v7, v11
	v_or_b32_e32 v6, 0x400, v10
	v_lshl_add_u64 v[18:19], v[8:9], 0, s[24:25]
	v_lshl_add_u64 v[16:17], v[8:9], 0, s[14:15]
	v_addc_co_u32_e32 v65, vcc, 0, v45, vcc
	v_lshl_add_u64 v[66:67], v[18:19], 0, v[10:11]
	v_lshl_add_u64 v[68:69], v[16:17], 0, v[10:11]
	v_lshl_add_u64 v[70:71], v[18:19], 0, v[6:7]
	v_lshl_add_u64 v[72:73], v[16:17], 0, v[6:7]
	global_load_dwordx4 v[44:47], v[64:65], off
	global_load_dwordx4 v[48:51], v[64:65], off offset:1024
	global_load_dwordx4 v[52:55], v[64:65], off offset:2048
	global_load_dwordx4 v[6:9], v[64:65], off offset:3072
	global_load_dwordx4 v[56:59], v[68:69], off
	global_load_dwordx4 v[60:63], v[66:67], off
	global_load_dwordx4 v[110:113], v[72:73], off
	global_load_dwordx4 v[114:117], v[70:71], off
	global_load_dwordx4 v[118:121], v10, s[28:29] offset:1024
	v_mov_b32_e32 v123, v11
	v_or_b32_e32 v122, 0x800, v10
	v_lshl_add_u64 v[122:123], v[16:17], 0, v[122:123]
	global_load_dwordx4 v[124:127], v[122:123], off
	v_mov_b32_e32 v123, v11
	v_or_b32_e32 v122, 0x800, v10
	v_lshl_add_u64 v[128:129], v[18:19], 0, v[122:123]
	global_load_dwordx4 v[130:133], v[128:129], off
	global_load_dwordx4 v[134:137], v10, s[28:29] offset:2048
	global_load_dwordx4 v[138:141], v10, s[28:29] offset:3072
	v_or_b32_e32 v142, 0xc00, v10
	v_mov_b32_e32 v143, v11
	v_lshl_add_u64 v[144:145], v[16:17], 0, v[142:143]
	global_load_dwordx4 v[146:149], v[144:145], off
	v_or_b32_e32 v142, 0xc00, v10
	v_mov_b32_e32 v143, v11
	v_lshl_add_u64 v[150:151], v[18:19], 0, v[142:143]
	global_load_dwordx4 v[152:155], v[150:151], off
	v_add_u32_e32 v1, s11, v1
	s_waitcnt vmcnt(18)
	v_mov_b32_e32 v66, v33
	s_waitcnt vmcnt(17)
	v_mov_b32_e32 v67, v37
	s_waitcnt vmcnt(16)
	v_mov_b32_e32 v78, v41
	s_waitcnt vmcnt(15)
	v_mov_b32_e32 v79, v3
	v_mov_b32_e32 v64, v32
	v_mov_b32_e32 v65, v36
	v_mov_b32_e32 v76, v40
	v_mov_b32_e32 v77, v2
	v_pk_mul_f32 v[66:67], v[66:67], v[66:67]
	v_pk_mul_f32 v[78:79], v[78:79], v[78:79]
	v_mov_b32_e32 v68, v34
	s_waitcnt vmcnt(14)
	v_mov_b32_e32 v86, v45
	s_waitcnt vmcnt(13)
	v_mov_b32_e32 v87, v49
	v_mov_b32_e32 v84, v44
	v_mov_b32_e32 v85, v48
	s_waitcnt vmcnt(12)
	v_mov_b32_e32 v94, v53
	s_waitcnt vmcnt(11)
	v_mov_b32_e32 v95, v7
	s_waitcnt vmcnt(10)
	v_add_f32_e32 v108, 1.0, v58
	v_add_f32_e32 v109, 1.0, v59
	v_pk_mul_f32 v[58:59], v[86:87], v[86:87]
	v_mov_b32_e32 v69, v38
	v_mov_b32_e32 v88, v46
	v_mov_b32_e32 v89, v50
	v_mov_b32_e32 v92, v52
	v_mov_b32_e32 v93, v6
	v_add_f32_e32 v106, 1.0, v56
	v_add_f32_e32 v107, 1.0, v57
	v_pk_fma_f32 v[56:57], v[64:65], v[64:65], v[66:67]
	v_pk_fma_f32 v[64:65], v[76:77], v[76:77], v[78:79]
	v_pk_mul_f32 v[66:67], v[94:95], v[94:95]
	v_mul_f32_e32 v78, v30, v108
	v_mul_f32_e32 v79, v31, v109
	v_pk_fma_f32 v[30:31], v[84:85], v[84:85], v[58:59]
	v_mov_b32_e32 v74, v35
	v_mov_b32_e32 v75, v39
	v_mov_b32_e32 v80, v42
	v_mov_b32_e32 v81, v4
	v_mov_b32_e32 v90, v47
	v_mov_b32_e32 v91, v51
	v_mov_b32_e32 v96, v54
	v_mov_b32_e32 v97, v8
	v_mul_f32_e32 v76, v28, v106
	v_mul_f32_e32 v77, v29, v107
	v_pk_fma_f32 v[28:29], v[68:69], v[68:69], v[56:57]
	v_pk_fma_f32 v[58:59], v[92:93], v[92:93], v[66:67]
	v_pk_fma_f32 v[30:31], v[88:89], v[88:89], v[30:31]
	v_mov_b32_e32 v82, v43
	v_mov_b32_e32 v83, v5
	v_mov_b32_e32 v98, v55
	v_mov_b32_e32 v99, v9
	v_pk_fma_f32 v[56:57], v[80:81], v[80:81], v[64:65]
	v_pk_fma_f32 v[28:29], v[74:75], v[74:75], v[28:29]
	v_pk_fma_f32 v[58:59], v[96:97], v[96:97], v[58:59]
	v_pk_fma_f32 v[30:31], v[90:91], v[90:91], v[30:31]
	v_pk_fma_f32 v[56:57], v[82:83], v[82:83], v[56:57]
	v_pk_fma_f32 v[58:59], v[98:99], v[98:99], v[58:59]
	v_mov_b32_e32 v65, v28
	v_mov_b32_e32 v64, v30
	v_mov_b32_e32 v28, v31
	v_mov_b32_e32 v67, v56
	v_mov_b32_e32 v66, v58
	v_pk_add_f32 v[28:29], v[64:65], v[28:29]
	v_mov_b32_e32 v56, v59
	v_pk_add_f32 v[28:29], v[28:29], v[66:67]
	s_nop 0
	v_pk_add_f32 v[28:29], v[28:29], v[56:57]
	ds_bpermute_b32 v31, v100, v29
	ds_bpermute_b32 v30, v100, v28
	v_mov_b32_e32 v57, v11
	v_or_b32_e32 v56, 0x800, v10
	v_lshl_add_u64 v[58:59], v[18:19], 0, v[56:57]
	v_lshl_add_u64 v[56:57], v[16:17], 0, v[56:57]
	s_waitcnt lgkmcnt(0)
	v_pk_add_f32 v[28:29], v[28:29], v[30:31]
	ds_bpermute_b32 v31, v101, v29
	ds_bpermute_b32 v30, v101, v28
	s_waitcnt lgkmcnt(0)
	v_pk_add_f32 v[28:29], v[28:29], v[30:31]
	ds_bpermute_b32 v31, v102, v29
	ds_bpermute_b32 v30, v102, v28
	s_waitcnt lgkmcnt(0)
	v_pk_add_f32 v[28:29], v[28:29], v[30:31]
	ds_bpermute_b32 v31, v103, v29
	ds_bpermute_b32 v30, v103, v28
	s_waitcnt lgkmcnt(0)
	v_pk_add_f32 v[28:29], v[28:29], v[30:31]
	ds_bpermute_b32 v31, v104, v29
	ds_bpermute_b32 v30, v104, v28
	s_waitcnt lgkmcnt(0)
	v_pk_add_f32 v[28:29], v[28:29], v[30:31]
	ds_bpermute_b32 v31, v105, v29
	ds_bpermute_b32 v30, v105, v28
	s_waitcnt lgkmcnt(0)
	v_pk_add_f32 v[28:29], v[28:29], v[30:31]
	s_nop 0
	v_pk_fma_f32 v[28:29], v[28:29], s[26:27], v[12:13] op_sel_hi:[1,0,0]
	v_add_u32_e32 v13, s27, v13
	v_mul_f32_e32 v30, 0x4b800000, v29
	v_cmp_gt_f32_e64 s[2:3], s34, v29
	v_mul_f32_e32 v31, 0x4b800000, v28
	v_cmp_gt_f32_e32 vcc, s34, v28
	v_cndmask_b32_e64 v29, v29, v30, s[2:3]
	v_rsq_f32_e32 v29, v29
	v_cndmask_b32_e32 v28, v28, v31, vcc
	v_rsq_f32_e32 v28, v28
	v_mul_f32_e32 v30, 0x45800000, v29
	v_cndmask_b32_e64 v64, v29, v30, s[2:3]
	v_mul_f32_e32 v31, 0x45800000, v28
	v_cndmask_b32_e32 v65, v28, v31, vcc
	v_mul_f32_e32 v28, v32, v64
	v_mul_f32_e32 v29, v33, v64
	v_mul_f32_e32 v30, v34, v64
	v_mul_f32_e32 v31, v35, v64
	s_waitcnt vmcnt(9)
	v_fma_f32 v28, v28, v76, v60
	v_fma_f32 v29, v29, v77, v61
	v_mul_f32_e32 v32, v44, v65
	v_mul_f32_e32 v33, v45, v65
	v_mul_f32_e32 v34, v46, v65
	v_mul_f32_e32 v35, v47, v65
	v_fma_f32 v30, v30, v78, v62
	v_fma_f32 v31, v31, v79, v63
	v_cvt_pk_bf16_f32 v28, v28, v29
	v_cvt_pk_bf16_f32 v29, v30, v31
	v_fma_f32 v32, v32, v76, v60
	v_fma_f32 v33, v33, v77, v61
	v_fma_f32 v34, v34, v78, v62
	v_fmac_f32_e32 v63, v35, v79
	v_cvt_pk_bf16_f32 v30, v32, v33
	v_cvt_pk_bf16_f32 v31, v34, v63
	global_store_dwordx2 v[14:15], v[28:29], off
	global_store_dwordx2 v[14:15], v[30:31], off offset:2048
	s_nop 0
	v_mul_f32_e32 v36, v36, v64
	v_mul_f32_e32 v37, v37, v64
	v_mul_f32_e32 v38, v38, v64
	v_mul_f32_e32 v39, v39, v64
	v_mul_f32_e32 v48, v48, v65
	v_mul_f32_e32 v49, v49, v65
	v_mul_f32_e32 v50, v50, v65
	v_mul_f32_e32 v51, v51, v65
	v_mul_f32_e32 v40, v40, v64
	v_mul_f32_e32 v41, v41, v64
	v_mul_f32_e32 v42, v42, v64
	v_mul_f32_e32 v43, v43, v64
	v_mul_f32_e32 v2, v2, v64
	v_mul_f32_e32 v3, v3, v64
	v_cmp_lt_i32_e32 vcc, s35, v1
	v_mul_f32_e32 v4, v4, v64
	v_mul_f32_e32 v5, v5, v64
	s_or_b64 s[22:23], vcc, s[22:23]
	v_mul_f32_e32 v6, v6, v65
	v_mul_f32_e32 v7, v7, v65
	v_mul_f32_e32 v8, v8, v65
	v_mul_f32_e32 v9, v9, v65
	s_waitcnt vmcnt(10)
	v_add_f32_e32 v110, 1.0, v110
	v_add_f32_e32 v111, 1.0, v111
	v_add_f32_e32 v112, 1.0, v112
	v_add_f32_e32 v113, 1.0, v113
	s_waitcnt vmcnt(8)
	v_mul_f32_e32 v110, v118, v110
	v_mul_f32_e32 v111, v119, v111
	v_mul_f32_e32 v112, v120, v112
	v_mul_f32_e32 v113, v121, v113
	v_fma_f32 v36, v36, v110, v114
	v_fma_f32 v37, v37, v111, v115
	v_fma_f32 v38, v38, v112, v116
	v_fma_f32 v39, v39, v113, v117
	v_fma_f32 v114, v48, v110, v114
	v_fma_f32 v115, v49, v111, v115
	v_cvt_pk_bf16_f32 v28, v36, v37
	v_cvt_pk_bf16_f32 v29, v38, v39
	v_fma_f32 v116, v50, v112, v116
	v_fmac_f32_e32 v117, v51, v113
	v_cvt_pk_bf16_f32 v30, v114, v115
	v_cvt_pk_bf16_f32 v31, v116, v117
	global_store_dwordx2 v[14:15], v[28:29], off offset:512
	global_store_dwordx2 v[14:15], v[30:31], off offset:2560
	s_nop 0
	v_mul_f32_e32 v44, v52, v65
	v_mul_f32_e32 v45, v53, v65
	v_mul_f32_e32 v46, v54, v65
	v_mul_f32_e32 v47, v55, v65
	s_waitcnt vmcnt(9)
	v_add_f32_e32 v124, 1.0, v124
	v_add_f32_e32 v125, 1.0, v125
	v_add_f32_e32 v126, 1.0, v126
	v_add_f32_e32 v127, 1.0, v127
	s_waitcnt vmcnt(7)
	v_mul_f32_e32 v124, v134, v124
	v_mul_f32_e32 v125, v135, v125
	v_mul_f32_e32 v126, v136, v126
	v_mul_f32_e32 v127, v137, v127
	v_fma_f32 v36, v40, v124, v130
	v_fma_f32 v37, v41, v125, v131
	v_fma_f32 v38, v42, v126, v132
	v_fma_f32 v39, v43, v127, v133
	v_fma_f32 v130, v44, v124, v130
	v_fma_f32 v131, v45, v125, v131
	v_cvt_pk_bf16_f32 v28, v36, v37
	v_cvt_pk_bf16_f32 v29, v38, v39
	v_fma_f32 v132, v46, v126, v132
	v_fmac_f32_e32 v133, v47, v127
	v_cvt_pk_bf16_f32 v30, v130, v131
	v_cvt_pk_bf16_f32 v31, v132, v133
	global_store_dwordx2 v[14:15], v[28:29], off offset:1024
	global_store_dwordx2 v[14:15], v[30:31], off offset:3072
	v_or_b32_e32 v10, 0xc00, v10
	v_lshl_add_u64 v[38:39], v[16:17], 0, v[10:11]
	v_lshl_add_u64 v[36:37], v[18:19], 0, v[10:11]
	s_waitcnt vmcnt(7)
	v_add_f32_e32 v10, 1.0, v146
	v_add_f32_e32 v16, 1.0, v147
	v_add_f32_e32 v17, 1.0, v148
	v_add_f32_e32 v18, 1.0, v149
	v_mul_f32_e32 v10, v138, v10
	v_mul_f32_e32 v16, v139, v16
	v_mul_f32_e32 v17, v140, v17
	v_mul_f32_e32 v18, v141, v18
	s_waitcnt vmcnt(6)
	v_fma_f32 v2, v2, v10, v152
	v_fma_f32 v3, v3, v16, v153
	v_fma_f32 v4, v4, v17, v154
	v_fma_f32 v5, v5, v18, v155
	v_cvt_pk_bf16_f32 v2, v2, v3
	v_cvt_pk_bf16_f32 v3, v4, v5
	v_fma_f32 v6, v6, v10, v152
	v_fma_f32 v7, v7, v16, v153
	v_fma_f32 v8, v8, v17, v154
	v_fmac_f32_e32 v155, v9, v18
	v_cvt_pk_bf16_f32 v4, v6, v7
	v_cvt_pk_bf16_f32 v5, v8, v155
	global_store_dwordx2 v[14:15], v[2:3], off offset:1536
	global_store_dwordx2 v[14:15], v[4:5], off offset:3584
	s_andn2_b64 exec, exec, s[22:23]
	s_cbranch_execnz .LBB0_1079

.LBB0_1138:
	s_mov_b32 s98, 0
	v_mov_b32_e32 v255, 0x0
	v_bfe_u32 v1, v0, 0, 1
	v_lshlrev_b32_e32 v1, 7, v1
	v_xor_b32_e32 v255, v255, v1
	v_bfe_u32 v1, v0, 1, 3
	v_mul_u32_u24_e32 v1, 0x110, v1
	v_xor_b32_e32 v255, v255, v1
	v_bfe_u32 v1, v0, 4, 2
	v_lshlrev_b32_e32 v1, 4, v1
	v_xor_b32_e32 v255, v255, v1
	v_bfe_u32 v1, v0, 8, 1
	v_lshlrev_b32_e32 v1, 14, v1
	v_xor_b32_e32 v255, v255, v1
	v_add_u32_e32 v254, 0x10000, v255
	v_xor_b32_e32 v253, 0x880, v255
	v_xor_b32_e32 v252, 0x10880, v255
	v_mov_b32_e32 v251, 0x8000
	v_bfe_u32 v1, v0, 0, 1
	v_lshlrev_b32_e32 v1, 7, v1
	v_xor_b32_e32 v251, v251, v1
	v_bfe_u32 v1, v0, 1, 3
	v_mul_u32_u24_e32 v1, 0x110, v1
	v_xor_b32_e32 v251, v251, v1
	v_bfe_u32 v1, v0, 4, 2
	v_lshlrev_b32_e32 v1, 4, v1
	v_xor_b32_e32 v251, v251, v1
	v_bfe_u32 v1, v0, 6, 2
	v_lshlrev_b32_e32 v1, 13, v1
	v_xor_b32_e32 v251, v251, v1
	v_add_u32_e32 v250, 0x10000, v251
	v_xor_b32_e32 v249, 0x880, v251
	v_xor_b32_e32 v248, 0x10880, v251
	v_xor_b32_e32 v247, 0x40, v255
	v_xor_b32_e32 v246, 0x10040, v255
	v_xor_b32_e32 v245, 0x8c0, v255
	v_xor_b32_e32 v244, 0x108c0, v255
	v_xor_b32_e32 v243, 0x40, v251
	v_xor_b32_e32 v242, 0x10040, v251
	v_xor_b32_e32 v241, 0x8c0, v251
	v_xor_b32_e32 v237, 0x108c0, v251
	v_mov_b32_e32 v236, 0x0
	v_bfe_u32 v1, v0, 0, 4
	v_lshlrev_b32_e32 v1, 4, v1
	v_xor_b32_e32 v236, v236, v1
	v_bfe_u32 v1, v0, 4, 4
	v_mul_u32_u24_e32 v1, 0x110, v1
	v_xor_b32_e32 v236, v236, v1
	v_bfe_u32 v1, v0, 8, 1
	v_lshlrev_b32_e32 v1, 12, v1
	v_xor_b32_e32 v236, v236, v1
	v_add_u32_e32 v235, 0x10000, v236
	v_mov_b32_e32 v234, 0x0
	v_bfe_u32 v1, v0, 0, 3
	v_lshlrev_b32_e32 v1, 4, v1
	v_add_u32_e32 v234, v234, v1
	v_bfe_u32 v1, v0, 3, 6
	v_lshlrev_b32_e32 v1, 11, v1
	v_add_u32_e32 v234, v234, v1
	v_add_u32_e32 v233, 0x20000, v234
	v_add_u32_e32 v232, 0x40000, v234
	v_add_u32_e32 v231, 0x60000, v234
	v_mov_b32_e32 v1, v0
	s_mov_b32 s2, s10
	s_load_dword s8, s[0:1], 0xe0
	s_load_dwordx2 s[2:3], s[16:17], 0xd0
	s_waitcnt vmcnt(0)
	v_mov_b32_e32 v2, v0
	s_mov_b32 s27, 0
	s_waitcnt lgkmcnt(0)
	s_add_u32 s11, s2, 0x17f0000
	s_addc_u32 s24, s3, 0
	s_add_u32 s6, s2, 0x37f0000
	s_addc_u32 s7, s3, 0
	s_add_u32 s25, s2, 0x770000
	s_addc_u32 s26, s3, 0
	s_lshr_b32 s28, s8, 3
	v_cvt_f32_u32_e32 v1, s28
	s_sub_i32 s8, 0, s28
	s_mov_b32 s2, s10
	v_rcp_iflag_f32_e32 v1, v1
	s_ashr_i32 s3, s2, 3
	s_abs_i32 s3, s3
	s_ashr_i32 s2, s2, 31
	v_mul_f32_e32 v1, 0x4f7ffffe, v1
	v_cvt_u32_f32_e32 v1, v1
	s_nop 0
	v_readfirstlane_b32 s30, v1
	s_mul_i32 s8, s8, s30
	s_mul_hi_u32 s8, s30, s8
	s_add_i32 s30, s30, s8
	s_mul_hi_u32 s8, s3, s30
	s_mul_i32 s8, s8, s28
	s_sub_i32 s3, s3, s8
	s_sub_i32 s8, s3, s28
	s_cmp_ge_u32 s3, s28
	s_cselect_b32 s3, s8, s3
	s_sub_i32 s8, s3, s28
	s_cmp_ge_u32 s3, s28
	s_cselect_b32 s3, s8, s3
	s_xor_b32 s3, s3, s2
	s_sub_i32 s31, s3, s2
	s_mul_hi_u32 s3, s30, 0xb0
	s_mul_i32 s3, s3, s28
	s_sub_i32 s3, 0xb0, s3
	s_sub_i32 s8, s3, s28
	s_cmp_ge_u32 s3, s28
	s_cselect_b32 s3, s8, s3
	s_sub_i32 s8, s3, s28
	s_cmp_ge_u32 s3, s28
	s_cselect_b32 s29, s8, s3
	s_sub_i32 s33, 0xb0, s29
	s_mov_b32 s2, s10
	s_cmp_ge_i32 s31, s33
	s_cbranch_scc1 .LBB0_1187
	s_mov_b32 s9, s10
	s_cmpk_gt_i32 s31, 0x9f
	s_cbranch_scc0 .LBB0_1141
	s_lshl_b32 s2, s31, 2
	s_add_i32 s2, s2, 0x7ffffd80
	s_and_b32 s8, s2, 0x7ffffff8
	s_and_b32 s2, s31, 1
	s_or_b32 s34, s2, 20
	s_cbranch_execz .LBB0_1142
	s_branch .LBB0_1143

.LBB0_1187:
	s_mov_b32 s98, 0
	v_mov_b32_e32 v255, 0x0
	v_bfe_u32 v1, v0, 0, 1
	v_lshlrev_b32_e32 v1, 7, v1
	v_xor_b32_e32 v255, v255, v1
	v_bfe_u32 v1, v0, 1, 3
	v_mul_u32_u24_e32 v1, 0x110, v1
	v_xor_b32_e32 v255, v255, v1
	v_bfe_u32 v1, v0, 4, 2
	v_lshlrev_b32_e32 v1, 4, v1
	v_xor_b32_e32 v255, v255, v1
	v_bfe_u32 v1, v0, 8, 1
	v_lshlrev_b32_e32 v1, 13, v1
	v_xor_b32_e32 v255, v255, v1
	v_add_u32_e32 v254, 0x10000, v255
	v_xor_b32_e32 v253, 0x880, v255
	v_xor_b32_e32 v252, 0x10880, v255
	v_mov_b32_e32 v251, 0x8000
	v_bfe_u32 v1, v0, 0, 1
	v_lshlrev_b32_e32 v1, 7, v1
	v_xor_b32_e32 v251, v251, v1
	v_bfe_u32 v1, v0, 1, 3
	v_mul_u32_u24_e32 v1, 0x110, v1
	v_xor_b32_e32 v251, v251, v1
	v_bfe_u32 v1, v0, 4, 2
	v_lshlrev_b32_e32 v1, 4, v1
	v_xor_b32_e32 v251, v251, v1
	v_bfe_u32 v1, v0, 6, 2
	v_lshlrev_b32_e32 v1, 13, v1
	v_xor_b32_e32 v251, v251, v1
	v_add_u32_e32 v250, 0x10000, v251
	v_xor_b32_e32 v249, 0x880, v251
	v_xor_b32_e32 v248, 0x10880, v251
	v_xor_b32_e32 v247, 0x40, v255
	v_xor_b32_e32 v246, 0x10040, v255
	v_xor_b32_e32 v245, 0x8c0, v255
	v_xor_b32_e32 v244, 0x108c0, v255
	v_xor_b32_e32 v243, 0x40, v251
	v_xor_b32_e32 v242, 0x10040, v251
	v_xor_b32_e32 v241, 0x8c0, v251
	v_xor_b32_e32 v240, 0x108c0, v251
	v_mov_b32_e32 v239, 0x0
	v_bfe_u32 v1, v0, 0, 4
	v_lshlrev_b32_e32 v1, 4, v1
	v_xor_b32_e32 v239, v239, v1
	v_bfe_u32 v1, v0, 4, 4
	v_mul_u32_u24_e32 v1, 0x110, v1
	v_xor_b32_e32 v239, v239, v1
	v_bfe_u32 v1, v0, 8, 1
	v_lshlrev_b32_e32 v1, 12, v1
	v_xor_b32_e32 v239, v239, v1
	v_add_u32_e32 v238, 0x10000, v239
	v_mov_b32_e32 v237, 0x0
	v_bfe_u32 v1, v0, 0, 3
	v_lshlrev_b32_e32 v1, 4, v1
	v_add_u32_e32 v237, v237, v1
	v_bfe_u32 v1, v0, 3, 6
	v_lshlrev_b32_e32 v1, 11, v1
	v_add_u32_e32 v237, v237, v1
	v_add_u32_e32 v236, 0x20000, v237
	v_add_u32_e32 v235, 0x40000, v237
	v_add_u32_e32 v234, 0x60000, v237
	v_mov_b32_e32 v1, v0
	s_mov_b32 s2, s10
	s_ashr_i32 s3, s2, 3
	s_abs_i32 s3, s3
	s_mul_hi_u32 s8, s3, s30
	s_mul_i32 s8, s8, s28
	s_sub_i32 s3, s3, s8
	s_ashr_i32 s2, s2, 31
	s_sub_i32 s8, s3, s28
	s_cmp_ge_u32 s3, s28
	s_cselect_b32 s3, s8, s3
	s_sub_i32 s8, s3, s28
	s_cmp_ge_u32 s3, s28
	s_cselect_b32 s3, s8, s3
	s_xor_b32 s3, s3, s2
	s_sub_i32 s22, s3, s2
	s_mov_b32 s2, s10
	s_lshl_b32 s8, s29, 1
	s_cmp_lt_i32 s22, s8
	s_cselect_b64 s[2:3], -1, 0
	s_cmp_ge_i32 s22, s8
	s_mov_b32 s23, 1
	s_cbranch_scc1 .LBB0_1189
	s_lshl_b32 s8, s22, 7
	s_and_b32 s27, s8, 0x80
	s_ashr_i32 s8, s22, 1
	s_sub_i32 s8, s8, s29
	s_add_i32 s29, s8, 0xb1
	s_add_i32 s22, s8, 0xb0
	s_branch .LBB0_1190

.LBB0_1298:
	s_mov_b32 s98, 0
	v_mov_b32_e32 v255, 0x0
	v_bfe_u32 v1, v0, 0, 1
	v_lshlrev_b32_e32 v1, 7, v1
	v_xor_b32_e32 v255, v255, v1
	v_bfe_u32 v1, v0, 1, 3
	v_mul_u32_u24_e32 v1, 0x110, v1
	v_xor_b32_e32 v255, v255, v1
	v_bfe_u32 v1, v0, 4, 2
	v_lshlrev_b32_e32 v1, 4, v1
	v_xor_b32_e32 v255, v255, v1
	v_bfe_u32 v1, v0, 8, 1
	v_lshlrev_b32_e32 v1, 14, v1
	v_xor_b32_e32 v255, v255, v1
	v_add_u32_e32 v254, 0x10000, v255
	v_xor_b32_e32 v253, 0x880, v255
	v_xor_b32_e32 v252, 0x10880, v255
	v_mov_b32_e32 v251, 0x8000
	v_bfe_u32 v1, v0, 0, 1
	v_lshlrev_b32_e32 v1, 7, v1
	v_xor_b32_e32 v251, v251, v1
	v_bfe_u32 v1, v0, 1, 3
	v_mul_u32_u24_e32 v1, 0x110, v1
	v_xor_b32_e32 v251, v251, v1
	v_bfe_u32 v1, v0, 4, 2
	v_lshlrev_b32_e32 v1, 4, v1
	v_xor_b32_e32 v251, v251, v1
	v_bfe_u32 v1, v0, 6, 2
	v_lshlrev_b32_e32 v1, 13, v1
	v_xor_b32_e32 v251, v251, v1
	v_add_u32_e32 v250, 0x10000, v251
	v_xor_b32_e32 v249, 0x880, v251
	v_xor_b32_e32 v248, 0x10880, v251
	v_xor_b32_e32 v247, 0x40, v255
	v_xor_b32_e32 v246, 0x10040, v255
	v_xor_b32_e32 v245, 0x8c0, v255
	v_xor_b32_e32 v244, 0x108c0, v255
	v_xor_b32_e32 v243, 0x40, v251
	v_xor_b32_e32 v242, 0x10040, v251
	v_xor_b32_e32 v241, 0x8c0, v251
	v_xor_b32_e32 v237, 0x108c0, v251
	v_mov_b32_e32 v236, 0x0
	v_bfe_u32 v1, v0, 0, 4
	v_lshlrev_b32_e32 v1, 4, v1
	v_xor_b32_e32 v236, v236, v1
	v_bfe_u32 v1, v0, 4, 4
	v_mul_u32_u24_e32 v1, 0x110, v1
	v_xor_b32_e32 v236, v236, v1
	v_bfe_u32 v1, v0, 8, 1
	v_lshlrev_b32_e32 v1, 12, v1
	v_xor_b32_e32 v236, v236, v1
	v_add_u32_e32 v235, 0x10000, v236
	v_mov_b32_e32 v234, 0x0
	v_bfe_u32 v1, v0, 0, 3
	v_lshlrev_b32_e32 v1, 4, v1
	v_add_u32_e32 v234, v234, v1
	v_bfe_u32 v1, v0, 3, 6
	v_mul_u32_u24_e32 v1, 0x1600, v1
	v_add_u32_e32 v234, v234, v1
	v_add_u32_e32 v233, 0x58000, v234
	v_add_u32_e32 v232, 0xb0000, v234
	v_add_u32_e32 v231, 0x108000, v234
	v_mov_b32_e32 v1, v0
	s_load_dword s2, s[0:1], 0xe0
	s_mov_b32 s3, s10
	v_mov_b32_e32 v1, v0
	s_waitcnt lgkmcnt(0)
	s_lshr_b32 s11, s2, 3
	s_waitcnt vmcnt(0)
	v_cvt_f32_u32_e32 v2, s11
	s_mov_b32 s2, s10
	s_ashr_i32 s3, s2, 3
	v_rcp_iflag_f32_e32 v2, v2
	s_ashr_i32 s4, s2, 31
	s_sub_i32 s2, 0, s11
	s_abs_i32 s3, s3
	v_mul_f32_e32 v1, 0x4f7ffffe, v2
	v_cvt_u32_f32_e32 v1, v1
	s_mov_b32 s50, 0
	v_readfirstlane_b32 s5, v1
	s_mul_i32 s2, s2, s5
	s_mul_hi_u32 s2, s5, s2
	s_add_i32 s2, s5, s2
	s_mul_hi_u32 s5, s3, s2
	s_mul_i32 s5, s5, s11
	s_sub_i32 s3, s3, s5
	s_sub_i32 s5, s3, s11
	s_cmp_ge_u32 s3, s11
	s_cselect_b32 s3, s5, s3
	s_sub_i32 s5, s3, s11
	s_cmp_ge_u32 s3, s11
	s_cselect_b32 s3, s5, s3
	s_xor_b32 s3, s3, s4
	s_sub_i32 s28, s3, s4
	s_mov_b32 s3, s10
	s_cmp_gt_i32 s28, 31
	s_cbranch_scc1 .LBB0_1362
	s_load_dwordx4 s[4:7], s[16:17], 0xc8
	s_mov_b32 s3, s10
	v_mov_b32_e32 v82, 0
	v_mov_b32_e32 v1, v0
	s_waitcnt lgkmcnt(0)
	s_add_u32 s12, s4, 0x2000000
	s_addc_u32 s13, s5, 0
	s_add_u32 s14, s6, 0x9000
	s_addc_u32 s15, s7, 0
	s_add_u32 s29, s6, 0x37f0000
	s_addc_u32 s30, s7, 0
	s_add_u32 s31, s6, 0x1270000
	s_addc_u32 s33, s7, 0
	s_ashr_i32 s6, s28, 31
	s_lshr_b32 s6, s6, 27
	s_add_i32 s6, s28, s6
	s_ashr_i32 s6, s6, 5
	s_lshl_b32 s7, s28, 1
	s_lshl_b32 s20, s6, 6
	s_sub_i32 s7, s7, s20
	s_lshl_b32 s6, s6, 2
	s_and_b32 s20, s28, 3
	s_or_b32 s34, s6, s20
	s_sub_i32 s6, s11, s28
	s_add_i32 s6, s6, 31
	s_mul_hi_u32 s2, s6, s2
	s_mul_i32 s20, s2, s11
	s_sub_i32 s6, s6, s20
	s_add_i32 s20, s2, 1
	s_sub_i32 s21, s6, s11
	s_cmp_ge_u32 s6, s11
	s_cselect_b32 s2, s20, s2
	s_cselect_b32 s6, s21, s6
	s_add_i32 s20, s2, 1
	s_cmp_ge_u32 s6, s11
	s_cselect_b32 s41, s20, s2
	s_and_b32 s2, s3, 7
	s_and_b32 s3, s7, -8
	s_movk_i32 s35, 0xb00
	v_lshrrev_b32_e32 v2, 3, v1
	s_or_b32 s36, s2, s3
	s_lshl_b32 s2, s34, 8
	s_mul_i32 s3, s34, 0x160000
	v_mul_lo_u32 v2, v2, s35
	v_lshlrev_b32_e32 v1, 3, v1
	s_mul_hi_i32 s6, s2, 0x1600
	s_add_u32 s2, s31, s3
	v_and_or_b32 v1, v1, 56, v2
	v_mov_b32_e32 v239, 0
	s_addc_u32 s3, s33, s6
	v_lshlrev_b32_e32 v238, 1, v1
	v_lshl_add_u64 v[2:3], s[2:3], 0, v[238:239]
	s_mov_b32 s37, 0x108000
	v_add_co_u32_e32 v34, vcc, s37, v2
	s_mov_b32 s20, 0xb0000
	s_nop 0
	v_addc_co_u32_e32 v35, vcc, 0, v3, vcc
	v_add_co_u32_e32 v36, vcc, s20, v2
	s_lshl_b32 s6, s36, 8
	s_mul_i32 s7, s36, 0x160000
	v_addc_co_u32_e32 v37, vcc, 0, v3, vcc
	s_mov_b32 s38, 0x58000
	s_mul_hi_i32 s21, s6, 0x1600
	s_add_u32 s6, s29, s7
	v_add_co_u32_e32 v2, vcc, s38, v2
	s_addc_u32 s7, s30, s21
	s_nop 0
	v_addc_co_u32_e32 v3, vcc, 0, v3, vcc
	v_lshl_add_u64 v[22:23], s[6:7], 0, v[238:239]
	v_add_co_u32_e32 v24, vcc, s20, v22
	global_load_dwordx4 v[2:5], v[2:3], off
	s_nop 0
	v_addc_co_u32_e32 v25, vcc, 0, v23, vcc
	v_add_co_u32_e32 v26, vcc, s38, v22
	v_mov_b32_e32 v1, v0
	s_nop 0
	v_addc_co_u32_e32 v27, vcc, 0, v23, vcc
	v_add_co_u32_e32 v38, vcc, s37, v22
	global_load_dwordx4 v[6:9], v[24:25], off
	global_load_dwordx4 v[10:13], v[26:27], off
	global_load_dwordx4 v[14:17], v238, s[2:3]
	global_load_dwordx4 v[18:21], v238, s[6:7]
	v_addc_co_u32_e32 v39, vcc, 0, v23, vcc
	global_load_dwordx4 v[22:25], v[38:39], off
	global_load_dwordx4 v[26:29], v[36:37], off
	global_load_dwordx4 v[30:33], v[34:35], off
	s_movk_i32 s40, 0xf0
	v_ashrrev_i32_e32 v34, 4, v1
	v_xor_b32_e32 v1, v34, v1
	v_lshlrev_b32_e32 v34, 8, v34
	v_lshlrev_b32_e32 v1, 4, v1
	v_and_or_b32 v1, v1, s40, v34
	s_mov_b32 s39, 2
	s_mul_i32 s41, s41, 44
	s_movk_i32 s42, 0xff80
	s_mov_b32 s43, 0x10000
	s_mov_b32 s44, 0x11000
	s_movk_i32 s45, 0x1800
	s_movk_i32 s46, 0x1fff
	v_mov_b32_e32 v240, 0x8040
	s_mov_b32 s26, 2
	s_mov_b32 s47, s28
	s_mov_b32 s48, s34
	s_mov_b32 s49, s36
	v_mov_b32_e32 v83, v82
	v_mov_b32_e32 v84, v82
	v_mov_b32_e32 v85, v82
	v_mov_b32_e32 v102, v82
	v_mov_b32_e32 v103, v82
	v_mov_b32_e32 v104, v82
	v_mov_b32_e32 v105, v82
	v_mov_b32_e32 v106, v82
	v_mov_b32_e32 v107, v82
	v_mov_b32_e32 v108, v82
	v_mov_b32_e32 v109, v82
	v_mov_b32_e32 v110, v82
	v_mov_b32_e32 v111, v82
	v_mov_b32_e32 v112, v82
	v_mov_b32_e32 v113, v82
	s_waitcnt vmcnt(4)
	ds_write_b128 v1, v[14:17] offset:32768
	s_waitcnt vmcnt(3)
	ds_write_b128 v1, v[18:21]
	ds_write_b128 v1, v[2:5] offset:40960
	ds_write_b128 v1, v[10:13] offset:8192
	ds_write_b128 v1, v[6:9] offset:16384
	s_waitcnt vmcnt(2)
	ds_write_b128 v1, v[22:25] offset:24576
	s_waitcnt vmcnt(1)
	ds_write_b128 v1, v[26:29] offset:49152
	s_waitcnt vmcnt(0)
	ds_write_b128 v1, v[30:33] offset:57344
	v_mov_b32_e32 v1, v0
	v_mov_b32_e32 v114, v82
	v_lshrrev_b32_e32 v2, 3, v1
	v_mul_lo_u32 v2, v2, s35
	v_lshlrev_b32_e32 v1, 3, v1
	v_and_or_b32 v1, v1, 56, v2
	v_lshlrev_b32_e32 v238, 1, v1
	v_lshl_add_u64 v[10:11], s[2:3], 0, v[238:239]
	v_add_co_u32_e32 v12, vcc, s37, v10
	v_lshl_add_u64 v[16:17], s[6:7], 0, v[238:239]
	s_nop 0
	v_addc_co_u32_e32 v13, vcc, 0, v11, vcc
	v_add_co_u32_e32 v14, vcc, s20, v10
	v_mov_b32_e32 v1, 0x10000
	s_nop 0
	v_addc_co_u32_e32 v15, vcc, 0, v11, vcc
	global_load_dwordx4 v[2:5], v[12:13], off offset:128
	global_load_dwordx4 v[6:9], v[14:15], off offset:128
	v_add_co_u32_e32 v14, vcc, s38, v10
	v_mov_b32_e32 v115, v82
	s_nop 0
	v_addc_co_u32_e32 v15, vcc, 0, v11, vcc
	v_add_co_u32_e32 v22, vcc, s37, v16
	v_mov_b32_e32 v116, v82
	s_nop 0
	v_addc_co_u32_e32 v23, vcc, 0, v17, vcc
	v_add_co_u32_e32 v34, vcc, s20, v16
	global_load_dwordx4 v[10:13], v[14:15], off offset:128
	global_load_dwordx4 v[18:21], v[22:23], off offset:128
	v_addc_co_u32_e32 v35, vcc, 0, v17, vcc
	v_add_co_u32_e32 v36, vcc, s38, v16
	v_mov_b32_e32 v117, v82
	s_nop 0
	v_addc_co_u32_e32 v37, vcc, 0, v17, vcc
	global_load_dwordx4 v[22:25], v[34:35], off offset:128
	global_load_dwordx4 v[26:29], v[36:37], off offset:128
	global_load_dwordx4 v[14:17], v238, s[2:3] offset:128
	global_load_dwordx4 v[30:33], v238, s[6:7] offset:128
	v_mov_b32_e32 v118, v82
	v_mov_b32_e32 v119, v82
	v_mov_b32_e32 v120, v82
	v_mov_b32_e32 v121, v82
	v_mov_b32_e32 v122, v82
	v_mov_b32_e32 v123, v82
	v_mov_b32_e32 v124, v82
	v_mov_b32_e32 v125, v82
	v_mov_b32_e32 v126, v82
	v_mov_b32_e32 v127, v82
	v_mov_b32_e32 v128, v82
	v_mov_b32_e32 v129, v82
	v_mov_b32_e32 v130, v82
	v_mov_b32_e32 v131, v82
	v_mov_b32_e32 v132, v82
	v_mov_b32_e32 v133, v82
	v_mov_b32_e32 v134, v82
	v_mov_b32_e32 v135, v82
	v_mov_b32_e32 v136, v82
	v_mov_b32_e32 v137, v82
	v_mov_b32_e32 v138, v82
	v_mov_b32_e32 v139, v82
	v_mov_b32_e32 v140, v82
	v_mov_b32_e32 v141, v82
	v_mov_b32_e32 v142, v82
	v_mov_b32_e32 v143, v82
	v_mov_b32_e32 v144, v82
	v_mov_b32_e32 v145, v82
	v_mov_b32_e32 v146, v82
	v_mov_b32_e32 v147, v82
	v_mov_b32_e32 v148, v82
	v_mov_b32_e32 v149, v82
	v_mov_b32_e32 v150, v82
	v_mov_b32_e32 v151, v82
	v_mov_b32_e32 v152, v82
	v_mov_b32_e32 v153, v82
	v_mov_b32_e32 v154, v82
	v_mov_b32_e32 v155, v82
	v_mov_b32_e32 v156, v82
	v_mov_b32_e32 v157, v82
	v_mov_b32_e32 v158, v82
	v_mov_b32_e32 v159, v82
	v_mov_b32_e32 v160, v82
	v_mov_b32_e32 v161, v82
	v_mov_b32_e32 v98, v82
	v_mov_b32_e32 v99, v82
	v_mov_b32_e32 v100, v82
	v_mov_b32_e32 v101, v82
	v_mov_b32_e32 v94, v82
	v_mov_b32_e32 v95, v82
	v_mov_b32_e32 v96, v82
	v_mov_b32_e32 v97, v82
	v_mov_b32_e32 v90, v82
	v_mov_b32_e32 v91, v82
	v_mov_b32_e32 v92, v82
	v_mov_b32_e32 v93, v82
	v_mov_b32_e32 v86, v82
	v_mov_b32_e32 v87, v82
	v_mov_b32_e32 v88, v82
	v_mov_b32_e32 v89, v82
	v_mov_b32_e32 v78, v82
	v_mov_b32_e32 v79, v82
	v_mov_b32_e32 v80, v82
	v_mov_b32_e32 v81, v82
	v_mov_b32_e32 v74, v82
	v_mov_b32_e32 v75, v82
	v_mov_b32_e32 v76, v82
	v_mov_b32_e32 v77, v82
	v_mov_b32_e32 v70, v82
	v_mov_b32_e32 v71, v82
	v_mov_b32_e32 v72, v82
	v_mov_b32_e32 v73, v82
	v_mov_b32_e32 v66, v82
	v_mov_b32_e32 v67, v82
	v_mov_b32_e32 v68, v82
	v_mov_b32_e32 v69, v82
	v_mov_b32_e32 v62, v82
	v_mov_b32_e32 v63, v82
	v_mov_b32_e32 v64, v82
	v_mov_b32_e32 v65, v82
	v_mov_b32_e32 v58, v82
	v_mov_b32_e32 v59, v82
	v_mov_b32_e32 v60, v82
	v_mov_b32_e32 v61, v82
	v_mov_b32_e32 v54, v82
	v_mov_b32_e32 v55, v82
	v_mov_b32_e32 v56, v82
	v_mov_b32_e32 v57, v82
	v_mov_b32_e32 v50, v82
	v_mov_b32_e32 v51, v82
	v_mov_b32_e32 v52, v82
	v_mov_b32_e32 v53, v82
	v_mov_b32_e32 v46, v82
	v_mov_b32_e32 v47, v82
	v_mov_b32_e32 v48, v82
	v_mov_b32_e32 v49, v82
	v_mov_b32_e32 v42, v82
	v_mov_b32_e32 v43, v82
	v_mov_b32_e32 v44, v82
	v_mov_b32_e32 v45, v82
	v_mov_b32_e32 v38, v82
	v_mov_b32_e32 v39, v82
	v_mov_b32_e32 v40, v82
	v_mov_b32_e32 v41, v82
	v_mov_b32_e32 v34, v82
	v_mov_b32_e32 v35, v82
	v_mov_b32_e32 v36, v82
	v_mov_b32_e32 v37, v82
	s_waitcnt lgkmcnt(0)
	s_barrier
	s_waitcnt vmcnt(0)
	s_branch .LBB0_1302

.LBB0_1464:
	s_andn2_saveexec_b64 s[42:43], s[2:3]
	s_cbranch_execz .LBB0_1421
	v_mov_b32_e32 v4, v0
	v_add_u32_e32 v40, 0xffffe000, v37
	v_lshrrev_b32_e32 v2, 5, v4
	v_and_b32_e32 v2, 6, v2
	v_add_u32_e32 v38, v37, v2
	v_ashrrev_i32_e32 v39, 31, v38
	v_lshlrev_b32_e32 v4, 2, v4
	v_lshlrev_b64 v[2:3], 12, v[38:39]
	v_and_b32_e32 v92, 0xfc, v4
	v_lshl_add_u64 v[2:3], s[4:5], 0, v[2:3]
	v_lshlrev_b32_e32 v34, 2, v92
	v_lshl_add_u64 v[6:7], v[2:3], 0, v[34:35]
	global_load_dwordx4 v[26:29], v[6:7], off
	global_load_dwordx4 v[18:21], v[6:7], off offset:1024
	global_load_dwordx4 v[10:13], v[6:7], off offset:2048
	global_load_dwordx4 v[2:5], v[6:7], off offset:3072
	v_add_co_u32_e32 v6, vcc, s73, v6
	v_xor_b32_e32 v41, 32, v46
	s_nop 0
	v_addc_co_u32_e32 v7, vcc, 0, v7, vcc
	global_load_dwordx4 v[30:33], v[6:7], off
	global_load_dwordx4 v[22:25], v[6:7], off offset:1024
	global_load_dwordx4 v[14:17], v[6:7], off offset:2048
	s_nop 0
	global_load_dwordx4 v[6:9], v[6:7], off offset:3072
	v_ashrrev_i32_e32 v40, 11, v40
	s_load_dwordx2 s[2:3], s[16:17], 0x48
	v_cmp_lt_i32_e32 vcc, v41, v47
	v_mad_i32_i24 v40, v40, s74, v44
	s_waitcnt lgkmcnt(0)
	s_add_u32 s44, s2, 0x1000
	v_cndmask_b32_e32 v41, v46, v41, vcc
	v_cmp_lt_i32_e32 vcc, s76, v38
	v_lshlrev_b32_e32 v93, 2, v41
	s_addc_u32 s45, s3, 0
	v_cndmask_b32_e32 v40, v45, v40, vcc
	v_ashrrev_i32_e32 v41, 31, v40
	v_lshl_add_u64 v[40:41], v[40:41], 2, s[14:15]
	v_lshl_add_u64 v[42:43], v[40:41], 0, s[38:39]
	v_lshl_add_u64 v[40:41], v[40:41], 0, v[34:35]
	v_lshl_add_u64 v[56:57], v[42:43], 0, v[34:35]
	global_load_dwordx4 v[48:51], v34, s[44:45]
	global_load_dwordx4 v[52:55], v[40:41], off
	s_nop 0
	global_load_dwordx4 v[56:59], v[56:57], off
	v_mov_b32_e32 v101, v35
	v_or_b32_e32 v100, 0x400, v34
	v_lshl_add_u64 v[102:103], v[42:43], 0, v[100:101]
	global_load_dwordx4 v[104:107], v[102:103], off
	v_or_b32_e32 v100, 0x400, v34
	global_load_dwordx4 v[108:111], v100, s[44:45]
	global_load_dwordx4 v[112:115], v[40:41], off offset:1024
	v_mov_b32_e32 v117, v35
	v_or_b32_e32 v116, 0x800, v34
	v_lshl_add_u64 v[118:119], v[42:43], 0, v[116:117]
	global_load_dwordx4 v[120:123], v[118:119], off
	v_or_b32_e32 v116, 0x800, v34
	global_load_dwordx4 v[124:127], v116, s[44:45]
	global_load_dwordx4 v[128:131], v[40:41], off offset:2048
	v_or_b32_e32 v132, 0xc00, v34
	v_mov_b32_e32 v133, v35
	v_lshl_add_u64 v[100:101], v[42:43], 0, v[132:133]
	global_load_dwordx4 v[134:137], v[100:101], off
	v_or_b32_e32 v132, 0xc00, v34
	global_load_dwordx4 v[138:141], v132, s[44:45]
	global_load_dwordx4 v[142:145], v[40:41], off offset:3072
	v_lshlrev_b64 v[38:39], 11, v[38:39]
	v_lshl_add_u64 v[38:39], s[20:21], 0, v[38:39]
	s_waitcnt vmcnt(19)
	v_mov_b32_e32 v62, v27
	s_waitcnt vmcnt(18)
	v_mov_b32_e32 v63, v19
	v_mov_b32_e32 v60, v26
	v_mov_b32_e32 v61, v18
	s_waitcnt vmcnt(17)
	v_mov_b32_e32 v70, v11
	s_waitcnt vmcnt(16)
	v_mov_b32_e32 v71, v3
	v_pk_mul_f32 v[62:63], v[62:63], v[62:63]
	s_waitcnt vmcnt(15)
	v_mov_b32_e32 v78, v31
	s_waitcnt vmcnt(14)
	v_mov_b32_e32 v79, v23
	v_mov_b32_e32 v68, v10
	v_mov_b32_e32 v69, v2
	v_mov_b32_e32 v76, v30
	v_mov_b32_e32 v77, v22
	v_pk_mul_f32 v[70:71], v[70:71], v[70:71]
	s_waitcnt vmcnt(13)
	v_mov_b32_e32 v86, v15
	s_waitcnt vmcnt(12)
	v_mov_b32_e32 v87, v7
	v_pk_fma_f32 v[60:61], v[60:61], v[60:61], v[62:63]
	v_pk_mul_f32 v[62:63], v[78:79], v[78:79]
	v_mov_b32_e32 v64, v28
	v_mov_b32_e32 v65, v20
	v_mov_b32_e32 v72, v12
	v_mov_b32_e32 v73, v4
	v_mov_b32_e32 v80, v32
	v_mov_b32_e32 v81, v24
	v_mov_b32_e32 v84, v14
	v_mov_b32_e32 v85, v6
	v_pk_fma_f32 v[68:69], v[68:69], v[68:69], v[70:71]
	v_pk_mul_f32 v[70:71], v[86:87], v[86:87]
	v_pk_fma_f32 v[62:63], v[76:77], v[76:77], v[62:63]
	v_mov_b32_e32 v66, v29
	v_mov_b32_e32 v67, v21
	v_mov_b32_e32 v82, v33
	v_mov_b32_e32 v83, v25
	v_mov_b32_e32 v88, v16
	v_mov_b32_e32 v89, v8
	v_pk_fma_f32 v[60:61], v[64:65], v[64:65], v[60:61]
	v_pk_fma_f32 v[64:65], v[72:73], v[72:73], v[68:69]
	v_pk_fma_f32 v[68:69], v[84:85], v[84:85], v[70:71]
	v_pk_fma_f32 v[62:63], v[80:81], v[80:81], v[62:63]
	v_mov_b32_e32 v74, v13
	v_mov_b32_e32 v75, v5
	v_mov_b32_e32 v90, v17
	v_mov_b32_e32 v91, v9
	v_pk_fma_f32 v[60:61], v[66:67], v[66:67], v[60:61]
	v_pk_fma_f32 v[66:67], v[88:89], v[88:89], v[68:69]
	v_pk_fma_f32 v[62:63], v[82:83], v[82:83], v[62:63]
	v_pk_fma_f32 v[64:65], v[74:75], v[74:75], v[64:65]
	v_pk_fma_f32 v[66:67], v[90:91], v[90:91], v[66:67]
	v_mov_b32_e32 v69, v60
	v_mov_b32_e32 v68, v62
	v_mov_b32_e32 v60, v63
	v_mov_b32_e32 v62, v66
	v_pk_add_f32 v[60:61], v[68:69], v[60:61]
	v_mov_b32_e32 v63, v64
	v_pk_add_f32 v[60:61], v[60:61], v[62:63]
	v_mov_b32_e32 v64, v67
	v_pk_add_f32 v[60:61], v[60:61], v[64:65]
	ds_bpermute_b32 v63, v93, v61
	ds_bpermute_b32 v62, v93, v60
	v_xor_b32_e32 v64, 16, v46
	v_cmp_lt_i32_e32 vcc, v64, v47
	s_waitcnt vmcnt(9)
	v_add_f32_e32 v56, 1.0, v56
	v_mul_f32_e32 v48, v48, v56
	v_cndmask_b32_e32 v64, v46, v64, vcc
	v_lshlrev_b32_e32 v64, 2, v64
	s_waitcnt lgkmcnt(0)
	v_pk_add_f32 v[60:61], v[60:61], v[62:63]
	ds_bpermute_b32 v63, v64, v61
	ds_bpermute_b32 v62, v64, v60
	v_xor_b32_e32 v64, 8, v46
	v_cmp_lt_i32_e32 vcc, v64, v47
	v_add_f32_e32 v56, 1.0, v57
	v_mul_f32_e32 v49, v49, v56
	v_cndmask_b32_e32 v64, v46, v64, vcc
	v_lshlrev_b32_e32 v64, 2, v64
	s_waitcnt lgkmcnt(0)
	v_pk_add_f32 v[60:61], v[60:61], v[62:63]
	ds_bpermute_b32 v63, v64, v61
	ds_bpermute_b32 v62, v64, v60
	v_xor_b32_e32 v64, 4, v46
	v_cmp_lt_i32_e32 vcc, v64, v47
	v_add_f32_e32 v56, 1.0, v58
	v_mul_f32_e32 v50, v50, v56
	v_cndmask_b32_e32 v64, v46, v64, vcc
	v_lshlrev_b32_e32 v64, 2, v64
	s_waitcnt lgkmcnt(0)
	v_pk_add_f32 v[60:61], v[60:61], v[62:63]
	ds_bpermute_b32 v63, v64, v61
	ds_bpermute_b32 v62, v64, v60
	v_xor_b32_e32 v64, 2, v46
	v_cmp_lt_i32_e32 vcc, v64, v47
	v_add_f32_e32 v56, 1.0, v59
	v_mul_f32_e32 v51, v51, v56
	v_cndmask_b32_e32 v64, v46, v64, vcc
	v_lshlrev_b32_e32 v64, 2, v64
	s_waitcnt lgkmcnt(0)
	v_pk_add_f32 v[60:61], v[60:61], v[62:63]
	ds_bpermute_b32 v63, v64, v61
	ds_bpermute_b32 v62, v64, v60
	v_xor_b32_e32 v64, 1, v46
	v_cmp_lt_i32_e32 vcc, v64, v47
	s_waitcnt lgkmcnt(0)
	v_pk_add_f32 v[60:61], v[60:61], v[62:63]
	v_cndmask_b32_e32 v64, v46, v64, vcc
	v_lshlrev_b32_e32 v64, 2, v64
	ds_bpermute_b32 v63, v64, v61
	ds_bpermute_b32 v62, v64, v60
	s_waitcnt lgkmcnt(0)
	v_pk_add_f32 v[60:61], v[60:61], v[62:63]
	s_nop 0
	v_pk_fma_f32 v[60:61], v[60:61], s[40:41], v[36:37] op_sel_hi:[1,0,0]
	s_nop 0
	v_mul_f32_e32 v62, 0x4b800000, v61
	v_cmp_gt_f32_e32 vcc, s77, v61
	v_cmp_gt_f32_e64 s[2:3], s77, v60
	s_nop 0
	v_cndmask_b32_e32 v61, v61, v62, vcc
	v_rsq_f32_e32 v61, v61
	v_mul_f32_e32 v62, 0x4b800000, v60
	v_cndmask_b32_e64 v60, v60, v62, s[2:3]
	v_rsq_f32_e32 v60, v60
	v_mul_f32_e32 v62, 0x45800000, v61
	v_cndmask_b32_e32 v61, v61, v62, vcc
	v_mul_f32_e32 v26, v26, v61
	v_mul_f32_e32 v27, v27, v61
	v_fma_f32 v26, v26, v48, v52
	v_fma_f32 v27, v27, v49, v53
	v_mul_f32_e32 v62, 0x45800000, v60
	v_cvt_pk_bf16_f32 v26, v26, v27
	v_mul_f32_e32 v27, v28, v61
	v_mul_f32_e32 v28, v29, v61
	v_cndmask_b32_e64 v60, v60, v62, s[2:3]
	v_fma_f32 v27, v27, v50, v54
	v_fma_f32 v28, v28, v51, v55
	v_cvt_pk_bf16_f32 v27, v27, v28
	v_mul_f32_e32 v28, v30, v60
	v_mul_f32_e32 v29, v31, v60
	v_fma_f32 v28, v28, v48, v52
	v_fma_f32 v29, v29, v49, v53
	v_mul_f32_e32 v30, v33, v60
	v_cvt_pk_bf16_f32 v28, v28, v29
	v_mul_f32_e32 v29, v32, v60
	v_fmac_f32_e32 v55, v30, v51
	v_lshlrev_b32_e32 v30, 1, v92
	v_mov_b32_e32 v31, v35
	v_fma_f32 v29, v29, v50, v54
	v_lshl_add_u64 v[38:39], v[38:39], 0, v[30:31]
	v_or_b32_e32 v30, 0x400, v34
	v_cvt_pk_bf16_f32 v29, v29, v55
	global_store_dwordx2 v[38:39], v[26:27], off
	global_store_dwordx2 v[38:39], v[28:29], off offset:2048
	v_lshl_add_u64 v[26:27], v[42:43], 0, v[30:31]
	s_nop 0
	s_nop 0
	v_mul_f32_e32 v18, v18, v61
	v_mul_f32_e32 v19, v19, v61
	v_mul_f32_e32 v20, v20, v61
	v_mul_f32_e32 v21, v21, v61
	v_mov_b32_e32 v53, v35
	v_or_b32_e32 v52, 0x800, v34
	v_mul_f32_e32 v22, v22, v60
	v_mul_f32_e32 v23, v23, v60
	v_mul_f32_e32 v24, v24, v60
	v_mul_f32_e32 v25, v25, v60
	v_lshl_add_u64 v[54:55], v[42:43], 0, v[52:53]
	v_mul_f32_e32 v10, v10, v61
	v_mul_f32_e32 v11, v11, v61
	v_mul_f32_e32 v12, v12, v61
	v_mul_f32_e32 v13, v13, v61
	v_or_b32_e32 v34, 0xc00, v34
	v_mul_f32_e32 v14, v14, v60
	v_mul_f32_e32 v15, v15, v60
	v_mul_f32_e32 v16, v16, v60
	v_mul_f32_e32 v17, v17, v60
	v_mul_f32_e32 v2, v2, v61
	v_mul_f32_e32 v3, v3, v61
	v_mul_f32_e32 v4, v4, v61
	v_mul_f32_e32 v5, v5, v61
	v_mul_f32_e32 v6, v6, v60
	v_mul_f32_e32 v7, v7, v60
	v_mul_f32_e32 v8, v8, v60
	v_mul_f32_e32 v9, v9, v60
	s_waitcnt vmcnt(10)
	v_add_f32_e32 v104, 1.0, v104
	v_add_f32_e32 v105, 1.0, v105
	v_add_f32_e32 v106, 1.0, v106
	v_add_f32_e32 v107, 1.0, v107
	s_waitcnt vmcnt(9)
	v_mul_f32_e32 v104, v108, v104
	v_mul_f32_e32 v105, v109, v105
	v_mul_f32_e32 v106, v110, v106
	v_mul_f32_e32 v107, v111, v107
	s_waitcnt vmcnt(8)
	v_fma_f32 v18, v18, v104, v112
	v_fma_f32 v19, v19, v105, v113
	v_fma_f32 v20, v20, v106, v114
	v_fma_f32 v21, v21, v107, v115
	v_cvt_pk_bf16_f32 v18, v18, v19
	v_cvt_pk_bf16_f32 v19, v20, v21
	v_fma_f32 v22, v22, v104, v112
	v_fma_f32 v23, v23, v105, v113
	v_fma_f32 v24, v24, v106, v114
	v_fmac_f32_e32 v115, v25, v107
	v_cvt_pk_bf16_f32 v20, v22, v23
	v_cvt_pk_bf16_f32 v21, v24, v115
	global_store_dwordx2 v[38:39], v[18:19], off offset:512
	global_store_dwordx2 v[38:39], v[20:21], off offset:2560
	s_nop 0
	v_lshl_add_u64 v[30:31], v[42:43], 0, v[34:35]
	s_waitcnt vmcnt(9)
	v_add_f32_e32 v120, 1.0, v120
	v_add_f32_e32 v121, 1.0, v121
	v_add_f32_e32 v122, 1.0, v122
	v_add_f32_e32 v123, 1.0, v123
	s_waitcnt vmcnt(8)
	v_mul_f32_e32 v120, v124, v120
	v_mul_f32_e32 v121, v125, v121
	v_mul_f32_e32 v122, v126, v122
	v_mul_f32_e32 v123, v127, v123
	s_waitcnt vmcnt(7)
	v_fma_f32 v10, v10, v120, v128
	v_fma_f32 v11, v11, v121, v129
	v_fma_f32 v12, v12, v122, v130
	v_fma_f32 v13, v13, v123, v131
	v_cvt_pk_bf16_f32 v10, v10, v11
	v_cvt_pk_bf16_f32 v11, v12, v13
	v_fma_f32 v14, v14, v120, v128
	v_fma_f32 v15, v15, v121, v129
	v_fma_f32 v16, v16, v122, v130
	v_fmac_f32_e32 v131, v17, v123
	v_cvt_pk_bf16_f32 v12, v14, v15
	v_cvt_pk_bf16_f32 v13, v16, v131
	global_store_dwordx2 v[38:39], v[10:11], off offset:1024
	global_store_dwordx2 v[38:39], v[12:13], off offset:3072
	s_nop 0
	s_waitcnt vmcnt(8)
	v_add_f32_e32 v134, 1.0, v134
	v_add_f32_e32 v135, 1.0, v135
	v_add_f32_e32 v136, 1.0, v136
	v_add_f32_e32 v137, 1.0, v137
	s_waitcnt vmcnt(7)
	v_mul_f32_e32 v134, v138, v134
	v_mul_f32_e32 v135, v139, v135
	v_mul_f32_e32 v136, v140, v136
	v_mul_f32_e32 v137, v141, v137
	s_waitcnt vmcnt(6)
	v_fma_f32 v2, v2, v134, v142
	v_fma_f32 v3, v3, v135, v143
	v_fma_f32 v4, v4, v136, v144
	v_fma_f32 v5, v5, v137, v145
	v_cvt_pk_bf16_f32 v2, v2, v3
	v_cvt_pk_bf16_f32 v3, v4, v5
	v_fma_f32 v6, v6, v134, v142
	v_fma_f32 v7, v7, v135, v143
	v_fma_f32 v8, v8, v136, v144
	v_fmac_f32_e32 v145, v9, v137
	v_cvt_pk_bf16_f32 v4, v6, v7
	v_cvt_pk_bf16_f32 v5, v8, v145
	global_store_dwordx2 v[38:39], v[2:3], off offset:1536
	global_store_dwordx2 v[38:39], v[4:5], off offset:3584
	s_branch .LBB0_1421

.LBB0_1524:
	s_mov_b32 s98, 0
	v_mov_b32_e32 v255, 0x0
	v_bfe_u32 v1, v0, 0, 1
	v_lshlrev_b32_e32 v1, 7, v1
	v_xor_b32_e32 v255, v255, v1
	v_bfe_u32 v1, v0, 1, 3
	v_mul_u32_u24_e32 v1, 0x110, v1
	v_xor_b32_e32 v255, v255, v1
	v_bfe_u32 v1, v0, 4, 2
	v_lshlrev_b32_e32 v1, 4, v1
	v_xor_b32_e32 v255, v255, v1
	v_bfe_u32 v1, v0, 8, 1
	v_lshlrev_b32_e32 v1, 14, v1
	v_xor_b32_e32 v255, v255, v1
	v_add_u32_e32 v254, 0x10000, v255
	v_xor_b32_e32 v253, 0x880, v255
	v_xor_b32_e32 v252, 0x10880, v255
	v_mov_b32_e32 v251, 0x8000
	v_bfe_u32 v1, v0, 1, 3
	v_lshlrev_b32_e32 v1, 8, v1
	v_add_u32_e32 v251, v251, v1
	v_bfe_u32 v1, v0, 6, 2
	v_mul_u32_u24_e32 v1, 0x1800, v1
	v_add_u32_e32 v251, v251, v1
	v_mov_b32_e32 v2, 0x0
	v_bfe_u32 v1, v0, 0, 1
	v_lshlrev_b32_e32 v1, 7, v1
	v_xor_b32_e32 v2, v2, v1
	v_bfe_u32 v1, v0, 1, 3
	v_lshlrev_b32_e32 v1, 4, v1
	v_xor_b32_e32 v2, v2, v1
	v_bfe_u32 v1, v0, 4, 2
	v_lshlrev_b32_e32 v1, 4, v1
	v_xor_b32_e32 v2, v2, v1
	v_bfe_u32 v1, v0, 6, 1
	v_lshlrev_b32_e32 v1, 7, v1
	v_xor_b32_e32 v2, v2, v1
	v_add_u32_e32 v251, v251, v2
	v_add_u32_e32 v250, 0x10000, v251
	v_mov_b32_e32 v249, 0x8800
	v_bfe_u32 v1, v0, 1, 3
	v_lshlrev_b32_e32 v1, 8, v1
	v_add_u32_e32 v249, v249, v1
	v_bfe_u32 v1, v0, 6, 2
	v_mul_u32_u24_e32 v1, 0x1800, v1
	v_add_u32_e32 v249, v249, v1
	v_mov_b32_e32 v2, 0x80
	v_bfe_u32 v1, v0, 0, 1
	v_lshlrev_b32_e32 v1, 7, v1
	v_xor_b32_e32 v2, v2, v1
	v_bfe_u32 v1, v0, 1, 3
	v_lshlrev_b32_e32 v1, 4, v1
	v_xor_b32_e32 v2, v2, v1
	v_bfe_u32 v1, v0, 4, 2
	v_lshlrev_b32_e32 v1, 4, v1
	v_xor_b32_e32 v2, v2, v1
	v_bfe_u32 v1, v0, 6, 1
	v_lshlrev_b32_e32 v1, 7, v1
	v_xor_b32_e32 v2, v2, v1
	v_add_u32_e32 v249, v249, v2
	v_add_u32_e32 v248, 0x10000, v249
	v_xor_b32_e32 v247, 0x40, v255
	v_xor_b32_e32 v246, 0x10040, v255
	v_xor_b32_e32 v245, 0x8c0, v255
	v_xor_b32_e32 v244, 0x108c0, v255
	v_xor_b32_e32 v243, 0x40, v251
	v_xor_b32_e32 v242, 0x10040, v251
	v_xor_b32_e32 v241, 0x40, v249
	v_xor_b32_e32 v240, 0x10040, v249
	v_mov_b32_e32 v239, 0x0
	v_bfe_u32 v1, v0, 0, 4
	v_lshlrev_b32_e32 v1, 4, v1
	v_xor_b32_e32 v239, v239, v1
	v_bfe_u32 v1, v0, 4, 4
	v_mul_u32_u24_e32 v1, 0x110, v1
	v_xor_b32_e32 v239, v239, v1
	v_bfe_u32 v1, v0, 8, 1
	v_lshlrev_b32_e32 v1, 12, v1
	v_xor_b32_e32 v239, v239, v1
	v_add_u32_e32 v238, 0x10000, v239
	v_mov_b32_e32 v237, 0x0
	v_bfe_u32 v1, v0, 0, 3
	v_lshlrev_b32_e32 v1, 4, v1
	v_add_u32_e32 v237, v237, v1
	v_bfe_u32 v1, v0, 3, 6
	v_lshlrev_b32_e32 v1, 11, v1
	v_add_u32_e32 v237, v237, v1
	v_add_u32_e32 v236, 0x20000, v237
	v_add_u32_e32 v235, 0x40000, v237
	v_add_u32_e32 v234, 0x60000, v237
	v_mov_b32_e32 v1, v0
	s_load_dword s2, s[0:1], 0xe0
	s_mov_b32 s3, s10
	v_mov_b32_e32 v1, v0
	s_waitcnt lgkmcnt(0)
	s_lshr_b32 s11, s2, 3
	s_waitcnt vmcnt(0)
	v_cvt_f32_u32_e32 v2, s11
	s_mov_b32 s2, s10
	s_ashr_i32 s3, s2, 3
	v_rcp_iflag_f32_e32 v2, v2
	s_ashr_i32 s4, s2, 31
	s_sub_i32 s2, 0, s11
	s_abs_i32 s3, s3
	v_mul_f32_e32 v1, 0x4f7ffffe, v2
	v_cvt_u32_f32_e32 v1, v1
	s_mov_b32 s45, 0
	v_readfirstlane_b32 s5, v1
	s_mul_i32 s2, s2, s5
	s_mul_hi_u32 s2, s5, s2
	s_add_i32 s2, s5, s2
	s_mul_hi_u32 s5, s3, s2
	s_mul_i32 s5, s5, s11
	s_sub_i32 s3, s3, s5
	s_sub_i32 s5, s3, s11
	s_cmp_ge_u32 s3, s11
	s_cselect_b32 s3, s5, s3
	s_sub_i32 s5, s3, s11
	s_cmp_ge_u32 s3, s11
	s_cselect_b32 s3, s5, s3
	s_xor_b32 s3, s3, s4
	s_sub_i32 s24, s3, s4
	s_mov_b32 s3, s10
	s_cmpk_gt_i32 s24, 0x5f
	s_cbranch_scc1 .LBB0_1604
	s_load_dwordx2 s[4:5], s[16:17], 0xd0
	s_mov_b32 s3, s10
	v_mov_b32_e32 v54, 0
	v_mov_b32_e32 v1, v0
	s_waitcnt lgkmcnt(0)
	s_add_u32 s25, s4, 0x17f0000
	s_addc_u32 s26, s5, 0
	s_add_u32 s8, s4, 0x37f0000
	s_addc_u32 s9, s5, 0
	s_add_u32 s27, s4, 0x50000
	s_addc_u32 s28, s5, 0
	s_ashr_i32 s4, s24, 31
	s_lshr_b32 s4, s4, 27
	s_add_i32 s4, s24, s4
	s_ashr_i32 s4, s4, 5
	s_lshl_b32 s5, s24, 1
	s_lshl_b32 s12, s4, 6
	s_sub_i32 s5, s5, s12
	s_lshl_b32 s4, s4, 2
	s_and_b32 s12, s24, 3
	s_or_b32 s29, s4, s12
	s_sub_i32 s4, s11, s24
	s_addk_i32 s4, 0x5f
	s_mul_hi_u32 s2, s4, s2
	s_mul_i32 s12, s2, s11
	s_sub_i32 s4, s4, s12
	s_add_i32 s12, s2, 1
	s_sub_i32 s13, s4, s11
	s_cmp_ge_u32 s4, s11
	s_cselect_b32 s2, s12, s2
	s_cselect_b32 s4, s13, s4
	s_add_i32 s12, s2, 1
	s_cmp_ge_u32 s4, s11
	s_cselect_b32 s2, s12, s2
	s_and_b32 s3, s3, 7
	s_and_b32 s4, s5, -8
	s_lshl_b32 s30, s2, 4
	s_mul_i32 s2, s29, 0xc0
	s_or_b32 s31, s3, s4
	s_ashr_i32 s3, s2, 31
	s_lshl_b64 s[2:3], s[2:3], 11
	v_lshlrev_b32_e32 v2, 8, v1
	v_lshlrev_b32_e32 v1, 4, v1
	s_add_u32 s2, s27, s2
	v_and_b32_e32 v1, 0x70, v1
	s_movk_i32 s33, 0xf800
	v_mov_b32_e32 v175, 0
	s_addc_u32 s3, s28, s3
	v_and_or_b32 v174, v2, s33, v1
	s_lshl_b32 s4, s31, 8
	v_lshl_add_u64 v[2:3], s[2:3], 0, v[174:175]
	s_mov_b32 s12, 0x40000
	s_ashr_i32 s5, s4, 31
	v_add_co_u32_e32 v14, vcc, s12, v2
	s_lshl_b64 s[4:5], s[4:5], 11
	s_nop 0
	v_addc_co_u32_e32 v15, vcc, 0, v3, vcc
	s_mov_b32 s34, 0x20000
	s_add_u32 s4, s25, s4
	v_add_co_u32_e32 v16, vcc, s34, v2
	s_addc_u32 s5, s26, s5
	s_nop 0
	v_addc_co_u32_e32 v17, vcc, 0, v3, vcc
	global_load_dwordx4 v[2:5], v[14:15], off
	global_load_dwordx4 v[6:9], v[16:17], off
	global_load_dwordx4 v[10:13], v174, s[2:3]
	v_lshl_add_u64 v[14:15], s[4:5], 0, v[174:175]
	s_mov_b32 s13, 0x60000
	v_add_co_u32_e32 v30, vcc, s13, v14
	v_mov_b32_e32 v1, v0
	s_nop 0
	v_addc_co_u32_e32 v31, vcc, 0, v15, vcc
	v_add_co_u32_e32 v32, vcc, s12, v14
	s_movk_i32 s36, 0xf0
	s_nop 0
	v_addc_co_u32_e32 v33, vcc, 0, v15, vcc
	v_add_co_u32_e32 v34, vcc, s34, v14
	s_mov_b32 s35, 2
	s_nop 0
	v_addc_co_u32_e32 v35, vcc, 0, v15, vcc
	global_load_dwordx4 v[14:17], v174, s[4:5]
	global_load_dwordx4 v[18:21], v[34:35], off
	global_load_dwordx4 v[22:25], v[32:33], off
	global_load_dwordx4 v[26:29], v[30:31], off
	v_mov_b32_e32 v30, v0
	v_ashrrev_i32_e32 v31, 4, v1
	v_xor_b32_e32 v1, v31, v1
	v_lshlrev_b32_e32 v31, 8, v31
	v_lshlrev_b32_e32 v1, 4, v1
	v_and_or_b32 v1, v1, s36, v31
	s_movk_i32 s37, 0xff80
	s_mov_b32 s38, 0x10000
	s_mov_b32 s39, 0x18000
	s_movk_i32 s40, 0x8a0
	s_movk_i32 s41, 0x1140
	v_mov_b32_e32 v176, 0x18000
	s_mov_b32 s22, 2
	s_mov_b32 s42, s24
	s_mov_b32 s43, s29
	s_mov_b32 s44, s31
	v_mov_b32_e32 v55, v54
	v_mov_b32_e32 v56, v54
	v_mov_b32_e32 v57, v54
	v_mov_b32_e32 v82, v54
	v_mov_b32_e32 v83, v54
	v_mov_b32_e32 v84, v54
	v_mov_b32_e32 v85, v54
	v_mov_b32_e32 v86, v54
	v_mov_b32_e32 v87, v54
	v_mov_b32_e32 v88, v54
	v_mov_b32_e32 v89, v54
	v_mov_b32_e32 v90, v54
	v_mov_b32_e32 v91, v54
	v_mov_b32_e32 v92, v54
	v_mov_b32_e32 v93, v54
	v_mov_b32_e32 v94, v54
	v_mov_b32_e32 v95, v54
	v_mov_b32_e32 v96, v54
	v_mov_b32_e32 v97, v54
	s_waitcnt vmcnt(4)
	ds_write_b128 v1, v[10:13] offset:32768
	ds_write_b128 v1, v[6:9] offset:40960
	ds_write_b128 v1, v[2:5] offset:49152
	s_waitcnt vmcnt(3)
	ds_write_b128 v1, v[14:17]
	s_waitcnt vmcnt(2)
	ds_write_b128 v1, v[18:21] offset:8192
	s_waitcnt vmcnt(1)
	ds_write_b128 v1, v[22:25] offset:16384
	s_waitcnt vmcnt(0)
	ds_write_b128 v1, v[26:29] offset:24576
	v_mov_b32_e32 v98, v54
	v_lshlrev_b32_e32 v2, 4, v30
	v_lshlrev_b32_e32 v1, 8, v30
	v_and_b32_e32 v2, 0x70, v2
	v_and_or_b32 v174, v1, s33, v2
	v_lshl_add_u64 v[2:3], s[2:3], 0, v[174:175]
	v_add_co_u32_e32 v10, vcc, s12, v2
	v_mov_b32_e32 v1, 0x10000
	s_nop 0
	v_addc_co_u32_e32 v11, vcc, 0, v3, vcc
	v_add_co_u32_e32 v12, vcc, s34, v2
	v_mov_b32_e32 v99, v54
	s_nop 0
	v_addc_co_u32_e32 v13, vcc, 0, v3, vcc
	global_load_dwordx4 v[2:5], v[10:11], off offset:128
	global_load_dwordx4 v[6:9], v[12:13], off offset:128
	v_lshl_add_u64 v[10:11], s[4:5], 0, v[174:175]
	v_add_co_u32_e32 v12, vcc, s13, v10
	v_mov_b32_e32 v100, v54
	s_nop 0
	v_addc_co_u32_e32 v13, vcc, 0, v11, vcc
	v_add_co_u32_e32 v22, vcc, s12, v10
	v_mov_b32_e32 v101, v54
	s_nop 0
	v_addc_co_u32_e32 v23, vcc, 0, v11, vcc
	v_add_co_u32_e32 v30, vcc, s34, v10
	global_load_dwordx4 v[14:17], v[12:13], off offset:128
	global_load_dwordx4 v[18:21], v[22:23], off offset:128
	v_addc_co_u32_e32 v31, vcc, 0, v11, vcc
	global_load_dwordx4 v[10:13], v174, s[2:3] offset:128
	global_load_dwordx4 v[22:25], v[30:31], off offset:128
	global_load_dwordx4 v[26:29], v174, s[4:5] offset:128
	v_mov_b32_e32 v102, v54
	v_mov_b32_e32 v103, v54
	v_mov_b32_e32 v104, v54
	v_mov_b32_e32 v105, v54
	v_mov_b32_e32 v106, v54
	v_mov_b32_e32 v107, v54
	v_mov_b32_e32 v108, v54
	v_mov_b32_e32 v109, v54
	v_mov_b32_e32 v110, v54
	v_mov_b32_e32 v111, v54
	v_mov_b32_e32 v112, v54
	v_mov_b32_e32 v113, v54
	v_mov_b32_e32 v114, v54
	v_mov_b32_e32 v115, v54
	v_mov_b32_e32 v116, v54
	v_mov_b32_e32 v117, v54
	v_mov_b32_e32 v118, v54
	v_mov_b32_e32 v119, v54
	v_mov_b32_e32 v120, v54
	v_mov_b32_e32 v121, v54
	v_mov_b32_e32 v122, v54
	v_mov_b32_e32 v123, v54
	v_mov_b32_e32 v124, v54
	v_mov_b32_e32 v125, v54
	v_mov_b32_e32 v78, v54
	v_mov_b32_e32 v79, v54
	v_mov_b32_e32 v80, v54
	v_mov_b32_e32 v81, v54
	v_mov_b32_e32 v74, v54
	v_mov_b32_e32 v75, v54
	v_mov_b32_e32 v76, v54
	v_mov_b32_e32 v77, v54
	v_mov_b32_e32 v70, v54
	v_mov_b32_e32 v71, v54
	v_mov_b32_e32 v72, v54
	v_mov_b32_e32 v73, v54
	v_mov_b32_e32 v66, v54
	v_mov_b32_e32 v67, v54
	v_mov_b32_e32 v68, v54
	v_mov_b32_e32 v69, v54
	v_mov_b32_e32 v62, v54
	v_mov_b32_e32 v63, v54
	v_mov_b32_e32 v64, v54
	v_mov_b32_e32 v65, v54
	v_mov_b32_e32 v58, v54
	v_mov_b32_e32 v59, v54
	v_mov_b32_e32 v60, v54
	v_mov_b32_e32 v61, v54
	v_mov_b32_e32 v50, v54
	v_mov_b32_e32 v51, v54
	v_mov_b32_e32 v52, v54
	v_mov_b32_e32 v53, v54
	v_mov_b32_e32 v46, v54
	v_mov_b32_e32 v47, v54
	v_mov_b32_e32 v48, v54
	v_mov_b32_e32 v49, v54
	v_mov_b32_e32 v42, v54
	v_mov_b32_e32 v43, v54
	v_mov_b32_e32 v44, v54
	v_mov_b32_e32 v45, v54
	v_mov_b32_e32 v38, v54
	v_mov_b32_e32 v39, v54
	v_mov_b32_e32 v40, v54
	v_mov_b32_e32 v41, v54
	v_mov_b32_e32 v34, v54
	v_mov_b32_e32 v35, v54
	v_mov_b32_e32 v36, v54
	v_mov_b32_e32 v37, v54
	v_mov_b32_e32 v30, v54
	v_mov_b32_e32 v31, v54
	v_mov_b32_e32 v32, v54
	v_mov_b32_e32 v33, v54
	s_waitcnt lgkmcnt(0)
	s_barrier
	s_waitcnt vmcnt(0)
	s_branch .LBB0_1528

.LBB0_2199:
	s_mov_b32 s98, 0
	v_mov_b32_e32 v255, 0x0
	v_bfe_u32 v1, v0, 0, 1
	v_lshlrev_b32_e32 v1, 7, v1
	v_xor_b32_e32 v255, v255, v1
	v_bfe_u32 v1, v0, 1, 3
	v_mul_u32_u24_e32 v1, 0x110, v1
	v_xor_b32_e32 v255, v255, v1
	v_bfe_u32 v1, v0, 4, 2
	v_lshlrev_b32_e32 v1, 4, v1
	v_xor_b32_e32 v255, v255, v1
	v_bfe_u32 v1, v0, 8, 1
	v_lshlrev_b32_e32 v1, 14, v1
	v_xor_b32_e32 v255, v255, v1
	v_add_u32_e32 v254, 0x10000, v255
	v_xor_b32_e32 v253, 0x880, v255
	v_xor_b32_e32 v252, 0x10880, v255
	v_mov_b32_e32 v251, 0x8000
	v_bfe_u32 v1, v0, 0, 1
	v_lshlrev_b32_e32 v1, 7, v1
	v_xor_b32_e32 v251, v251, v1
	v_bfe_u32 v1, v0, 1, 3
	v_mul_u32_u24_e32 v1, 0x110, v1
	v_xor_b32_e32 v251, v251, v1
	v_bfe_u32 v1, v0, 4, 2
	v_lshlrev_b32_e32 v1, 4, v1
	v_xor_b32_e32 v251, v251, v1
	v_bfe_u32 v1, v0, 6, 2
	v_lshlrev_b32_e32 v1, 13, v1
	v_xor_b32_e32 v251, v251, v1
	v_add_u32_e32 v250, 0x10000, v251
	v_xor_b32_e32 v249, 0x880, v251
	v_xor_b32_e32 v248, 0x10880, v251
	v_xor_b32_e32 v247, 0x40, v255
	v_xor_b32_e32 v246, 0x10040, v255
	v_xor_b32_e32 v245, 0x8c0, v255
	v_xor_b32_e32 v244, 0x108c0, v255
	v_xor_b32_e32 v243, 0x40, v251
	v_xor_b32_e32 v242, 0x10040, v251
	v_xor_b32_e32 v241, 0x8c0, v251
	v_xor_b32_e32 v237, 0x108c0, v251
	v_mov_b32_e32 v236, 0x0
	v_bfe_u32 v1, v0, 0, 4
	v_lshlrev_b32_e32 v1, 4, v1
	v_xor_b32_e32 v236, v236, v1
	v_bfe_u32 v1, v0, 4, 4
	v_mul_u32_u24_e32 v1, 0x110, v1
	v_xor_b32_e32 v236, v236, v1
	v_bfe_u32 v1, v0, 8, 1
	v_lshlrev_b32_e32 v1, 12, v1
	v_xor_b32_e32 v236, v236, v1
	v_add_u32_e32 v235, 0x10000, v236
	v_mov_b32_e32 v234, 0x0
	v_bfe_u32 v1, v0, 0, 3
	v_lshlrev_b32_e32 v1, 4, v1
	v_add_u32_e32 v234, v234, v1
	v_bfe_u32 v1, v0, 3, 6
	v_lshlrev_b32_e32 v1, 11, v1
	v_add_u32_e32 v234, v234, v1
	v_add_u32_e32 v233, 0x20000, v234
	v_add_u32_e32 v232, 0x40000, v234
	v_add_u32_e32 v231, 0x60000, v234
	v_mov_b32_e32 v1, v0
	s_load_dword s2, s[0:1], 0xe0
	s_mov_b32 s3, s10
	v_mov_b32_e32 v1, v0
	s_waitcnt lgkmcnt(0)
	s_lshr_b32 s11, s2, 3
	s_waitcnt vmcnt(0)
	v_cvt_f32_u32_e32 v2, s11
	s_mov_b32 s2, s10
	s_ashr_i32 s3, s2, 3
	v_rcp_iflag_f32_e32 v2, v2
	s_ashr_i32 s4, s2, 31
	s_sub_i32 s2, 0, s11
	s_abs_i32 s3, s3
	v_mul_f32_e32 v1, 0x4f7ffffe, v2
	v_cvt_u32_f32_e32 v1, v1
	s_mov_b32 s50, 0
	v_readfirstlane_b32 s5, v1
	s_mul_i32 s2, s2, s5
	s_mul_hi_u32 s2, s5, s2
	s_add_i32 s2, s5, s2
	s_mul_hi_u32 s5, s3, s2
	s_mul_i32 s5, s5, s11
	s_sub_i32 s3, s3, s5
	s_sub_i32 s5, s3, s11
	s_cmp_ge_u32 s3, s11
	s_cselect_b32 s3, s5, s3
	s_sub_i32 s5, s3, s11
	s_cmp_ge_u32 s3, s11
	s_cselect_b32 s3, s5, s3
	s_xor_b32 s3, s3, s4
	s_sub_i32 s28, s3, s4
	s_mov_b32 s3, s10
	s_cmp_gt_i32 s28, 31
	s_cbranch_scc1 .LBB0_2263
	s_load_dwordx4 s[4:7], s[16:17], 0xc8
	s_mov_b32 s3, s10
	v_mov_b32_e32 v82, 0
	v_mov_b32_e32 v1, v0
	s_waitcnt lgkmcnt(0)
	s_add_u32 s29, s6, 0x17f0000
	s_addc_u32 s30, s7, 0
	s_add_u32 s12, s4, 0x2000000
	s_addc_u32 s13, s5, 0
	s_add_u32 s14, s6, 0x24000
	s_addc_u32 s15, s7, 0
	s_add_u32 s31, s6, 0x570000
	s_addc_u32 s33, s7, 0
	s_ashr_i32 s6, s28, 31
	s_lshr_b32 s6, s6, 27
	s_add_i32 s6, s28, s6
	s_ashr_i32 s6, s6, 5
	s_lshl_b32 s7, s28, 1
	s_lshl_b32 s20, s6, 6
	s_sub_i32 s7, s7, s20
	s_lshl_b32 s6, s6, 2
	s_and_b32 s20, s28, 3
	s_or_b32 s34, s6, s20
	s_sub_i32 s6, s11, s28
	s_add_i32 s6, s6, 31
	s_mul_hi_u32 s2, s6, s2
	s_mul_i32 s20, s2, s11
	s_sub_i32 s6, s6, s20
	s_add_i32 s20, s2, 1
	s_sub_i32 s21, s6, s11
	s_cmp_ge_u32 s6, s11
	s_cselect_b32 s2, s20, s2
	s_cselect_b32 s6, s21, s6
	s_add_i32 s20, s2, 1
	s_cmp_ge_u32 s6, s11
	s_cselect_b32 s2, s20, s2
	s_and_b32 s3, s3, 7
	s_and_b32 s6, s7, -8
	s_lshl_b32 s35, s2, 4
	s_lshl_b32 s2, s34, 8
	s_or_b32 s36, s3, s6
	s_ashr_i32 s3, s2, 31
	s_lshl_b64 s[2:3], s[2:3], 11
	v_lshlrev_b32_e32 v2, 8, v1
	v_lshlrev_b32_e32 v1, 4, v1
	s_add_u32 s2, s31, s2
	v_and_b32_e32 v1, 0x70, v1
	s_movk_i32 s37, 0xf800
	v_mov_b32_e32 v239, 0
	s_addc_u32 s3, s33, s3
	v_and_or_b32 v238, v2, s37, v1
	v_lshl_add_u64 v[10:11], s[2:3], 0, v[238:239]
	s_mov_b32 s38, 0x60000
	v_add_co_u32_e32 v12, vcc, s38, v10
	s_lshl_b32 s6, s36, 8
	s_nop 0
	v_addc_co_u32_e32 v13, vcc, 0, v11, vcc
	s_mov_b32 s20, 0x40000
	s_ashr_i32 s7, s6, 31
	v_add_co_u32_e32 v14, vcc, s20, v10
	s_lshl_b64 s[6:7], s[6:7], 11
	s_nop 0
	v_addc_co_u32_e32 v15, vcc, 0, v11, vcc
	s_mov_b32 s39, 0x20000
	s_add_u32 s6, s29, s6
	v_add_co_u32_e32 v18, vcc, s39, v10
	s_addc_u32 s7, s30, s7
	s_nop 0
	v_addc_co_u32_e32 v19, vcc, 0, v11, vcc
	v_lshl_add_u64 v[30:31], s[6:7], 0, v[238:239]
	v_add_co_u32_e32 v32, vcc, s20, v30
	global_load_dwordx4 v[2:5], v[12:13], off
	global_load_dwordx4 v[6:9], v[14:15], off
	v_addc_co_u32_e32 v33, vcc, 0, v31, vcc
	v_add_co_u32_e32 v34, vcc, s39, v30
	global_load_dwordx4 v[10:13], v[18:19], off
	global_load_dwordx4 v[14:17], v238, s[2:3]
	v_addc_co_u32_e32 v35, vcc, 0, v31, vcc
	global_load_dwordx4 v[18:21], v[32:33], off
	global_load_dwordx4 v[22:25], v[34:35], off
	global_load_dwordx4 v[26:29], v238, s[6:7]
	v_add_co_u32_e32 v30, vcc, s38, v30
	v_mov_b32_e32 v1, v0
	s_nop 0
	v_addc_co_u32_e32 v31, vcc, 0, v31, vcc
	global_load_dwordx4 v[30:33], v[30:31], off
	s_movk_i32 s41, 0xf0
	v_ashrrev_i32_e32 v35, 4, v1
	v_xor_b32_e32 v1, v35, v1
	v_lshlrev_b32_e32 v35, 8, v35
	v_lshlrev_b32_e32 v1, 4, v1
	v_mov_b32_e32 v34, v0
	v_and_or_b32 v1, v1, s41, v35
	s_mov_b32 s40, 2
	s_movk_i32 s42, 0xff80
	s_mov_b32 s43, 0x10000
	s_mov_b32 s44, 0x11000
	s_movk_i32 s45, 0x1800
	s_movk_i32 s46, 0x1fff
	v_mov_b32_e32 v240, 0x8040
	s_mov_b32 s26, 2
	s_mov_b32 s47, s28
	s_mov_b32 s48, s34
	s_mov_b32 s49, s36
	v_mov_b32_e32 v83, v82
	v_mov_b32_e32 v84, v82
	v_mov_b32_e32 v85, v82
	v_mov_b32_e32 v102, v82
	v_mov_b32_e32 v103, v82
	v_mov_b32_e32 v104, v82
	v_mov_b32_e32 v105, v82
	v_mov_b32_e32 v106, v82
	v_mov_b32_e32 v107, v82
	v_mov_b32_e32 v108, v82
	v_mov_b32_e32 v109, v82
	v_mov_b32_e32 v110, v82
	v_mov_b32_e32 v111, v82
	s_waitcnt vmcnt(4)
	ds_write_b128 v1, v[14:17] offset:32768
	ds_write_b128 v1, v[10:13] offset:40960
	ds_write_b128 v1, v[6:9] offset:49152
	ds_write_b128 v1, v[2:5] offset:57344
	s_waitcnt vmcnt(1)
	ds_write_b128 v1, v[26:29]
	ds_write_b128 v1, v[22:25] offset:8192
	ds_write_b128 v1, v[18:21] offset:16384
	s_waitcnt vmcnt(0)
	ds_write_b128 v1, v[30:33] offset:24576
	v_mov_b32_e32 v112, v82
	v_lshlrev_b32_e32 v2, 4, v34
	v_lshlrev_b32_e32 v1, 8, v34
	v_and_b32_e32 v2, 0x70, v2
	v_and_or_b32 v238, v1, s37, v2
	v_lshl_add_u64 v[10:11], s[2:3], 0, v[238:239]
	v_add_co_u32_e32 v12, vcc, s38, v10
	v_lshl_add_u64 v[16:17], s[6:7], 0, v[238:239]
	s_nop 0
	v_addc_co_u32_e32 v13, vcc, 0, v11, vcc
	v_add_co_u32_e32 v14, vcc, s20, v10
	v_mov_b32_e32 v1, 0x10000
	s_nop 0
	v_addc_co_u32_e32 v15, vcc, 0, v11, vcc
	global_load_dwordx4 v[2:5], v[12:13], off offset:128
	global_load_dwordx4 v[6:9], v[14:15], off offset:128
	v_add_co_u32_e32 v14, vcc, s39, v10
	v_mov_b32_e32 v113, v82
	s_nop 0
	v_addc_co_u32_e32 v15, vcc, 0, v11, vcc
	v_add_co_u32_e32 v22, vcc, s38, v16
	v_mov_b32_e32 v114, v82
	s_nop 0
	v_addc_co_u32_e32 v23, vcc, 0, v17, vcc
	v_add_co_u32_e32 v34, vcc, s20, v16
	global_load_dwordx4 v[10:13], v[14:15], off offset:128
	global_load_dwordx4 v[18:21], v[22:23], off offset:128
	v_addc_co_u32_e32 v35, vcc, 0, v17, vcc
	v_add_co_u32_e32 v36, vcc, s39, v16
	v_mov_b32_e32 v115, v82
	s_nop 0
	v_addc_co_u32_e32 v37, vcc, 0, v17, vcc
	global_load_dwordx4 v[22:25], v[34:35], off offset:128
	global_load_dwordx4 v[26:29], v[36:37], off offset:128
	global_load_dwordx4 v[14:17], v238, s[2:3] offset:128
	global_load_dwordx4 v[30:33], v238, s[6:7] offset:128
	v_mov_b32_e32 v116, v82
	v_mov_b32_e32 v117, v82
	v_mov_b32_e32 v118, v82
	v_mov_b32_e32 v119, v82
	v_mov_b32_e32 v120, v82
	v_mov_b32_e32 v121, v82
	v_mov_b32_e32 v122, v82
	v_mov_b32_e32 v123, v82
	v_mov_b32_e32 v124, v82
	v_mov_b32_e32 v125, v82
	v_mov_b32_e32 v126, v82
	v_mov_b32_e32 v127, v82
	v_mov_b32_e32 v128, v82
	v_mov_b32_e32 v129, v82
	v_mov_b32_e32 v130, v82
	v_mov_b32_e32 v131, v82
	v_mov_b32_e32 v132, v82
	v_mov_b32_e32 v133, v82
	v_mov_b32_e32 v134, v82
	v_mov_b32_e32 v135, v82
	v_mov_b32_e32 v136, v82
	v_mov_b32_e32 v137, v82
	v_mov_b32_e32 v138, v82
	v_mov_b32_e32 v139, v82
	v_mov_b32_e32 v140, v82
	v_mov_b32_e32 v141, v82
	v_mov_b32_e32 v142, v82
	v_mov_b32_e32 v143, v82
	v_mov_b32_e32 v144, v82
	v_mov_b32_e32 v145, v82
	v_mov_b32_e32 v146, v82
	v_mov_b32_e32 v147, v82
	v_mov_b32_e32 v148, v82
	v_mov_b32_e32 v149, v82
	v_mov_b32_e32 v150, v82
	v_mov_b32_e32 v151, v82
	v_mov_b32_e32 v152, v82
	v_mov_b32_e32 v153, v82
	v_mov_b32_e32 v154, v82
	v_mov_b32_e32 v155, v82
	v_mov_b32_e32 v156, v82
	v_mov_b32_e32 v157, v82
	v_mov_b32_e32 v158, v82
	v_mov_b32_e32 v159, v82
	v_mov_b32_e32 v160, v82
	v_mov_b32_e32 v161, v82
	v_mov_b32_e32 v98, v82
	v_mov_b32_e32 v99, v82
	v_mov_b32_e32 v100, v82
	v_mov_b32_e32 v101, v82
	v_mov_b32_e32 v94, v82
	v_mov_b32_e32 v95, v82
	v_mov_b32_e32 v96, v82
	v_mov_b32_e32 v97, v82
	v_mov_b32_e32 v90, v82
	v_mov_b32_e32 v91, v82
	v_mov_b32_e32 v92, v82
	v_mov_b32_e32 v93, v82
	v_mov_b32_e32 v86, v82
	v_mov_b32_e32 v87, v82
	v_mov_b32_e32 v88, v82
	v_mov_b32_e32 v89, v82
	v_mov_b32_e32 v78, v82
	v_mov_b32_e32 v79, v82
	v_mov_b32_e32 v80, v82
	v_mov_b32_e32 v81, v82
	v_mov_b32_e32 v74, v82
	v_mov_b32_e32 v75, v82
	v_mov_b32_e32 v76, v82
	v_mov_b32_e32 v77, v82
	v_mov_b32_e32 v70, v82
	v_mov_b32_e32 v71, v82
	v_mov_b32_e32 v72, v82
	v_mov_b32_e32 v73, v82
	v_mov_b32_e32 v66, v82
	v_mov_b32_e32 v67, v82
	v_mov_b32_e32 v68, v82
	v_mov_b32_e32 v69, v82
	v_mov_b32_e32 v62, v82
	v_mov_b32_e32 v63, v82
	v_mov_b32_e32 v64, v82
	v_mov_b32_e32 v65, v82
	v_mov_b32_e32 v58, v82
	v_mov_b32_e32 v59, v82
	v_mov_b32_e32 v60, v82
	v_mov_b32_e32 v61, v82
	v_mov_b32_e32 v54, v82
	v_mov_b32_e32 v55, v82
	v_mov_b32_e32 v56, v82
	v_mov_b32_e32 v57, v82
	v_mov_b32_e32 v50, v82
	v_mov_b32_e32 v51, v82
	v_mov_b32_e32 v52, v82
	v_mov_b32_e32 v53, v82
	v_mov_b32_e32 v46, v82
	v_mov_b32_e32 v47, v82
	v_mov_b32_e32 v48, v82
	v_mov_b32_e32 v49, v82
	v_mov_b32_e32 v42, v82
	v_mov_b32_e32 v43, v82
	v_mov_b32_e32 v44, v82
	v_mov_b32_e32 v45, v82
	v_mov_b32_e32 v38, v82
	v_mov_b32_e32 v39, v82
	v_mov_b32_e32 v40, v82
	v_mov_b32_e32 v41, v82
	v_mov_b32_e32 v34, v82
	v_mov_b32_e32 v35, v82
	v_mov_b32_e32 v36, v82
	v_mov_b32_e32 v37, v82
	s_waitcnt lgkmcnt(0)
	s_barrier
	s_waitcnt vmcnt(0)
	s_branch .LBB0_2203

.LBB0_2322:
	v_cmp_lt_i32_e32 vcc, v32, v31
	v_mov_b32_e32 v2, v0
	v_add_u32_e32 v4, 0xffffe000, v21
	v_cndmask_b32_e32 v5, v30, v32, vcc
	v_cmp_lt_i32_e32 vcc, v33, v31
	v_ashrrev_i32_e32 v4, 11, v4
	s_load_dwordx2 s[2:3], s[16:17], 0x50
	v_cndmask_b32_e32 v6, v30, v33, vcc
	v_cmp_lt_i32_e32 vcc, v34, v31
	v_lshlrev_b32_e32 v104, 2, v5
	v_lshrrev_b32_e32 v5, 5, v2
	v_cndmask_b32_e32 v7, v30, v34, vcc
	v_cmp_lt_i32_e32 vcc, v35, v31
	v_lshlrev_b32_e32 v105, 2, v6
	v_mad_i32_i24 v6, v4, s30, v28
	v_and_b32_e32 v4, 6, v5
	v_cndmask_b32_e32 v8, v30, v35, vcc
	v_cmp_lt_i32_e32 vcc, v36, v31
	v_add_u32_e32 v4, v21, v4
	v_lshlrev_b32_e32 v2, 2, v2
	v_cndmask_b32_e32 v9, v30, v36, vcc
	v_cmp_lt_i32_e32 vcc, v37, v31
	v_ashrrev_i32_e32 v5, 31, v4
	v_lshlrev_b32_e32 v107, 2, v8
	v_cndmask_b32_e32 v10, v30, v37, vcc
	v_lshlrev_b32_e32 v108, 2, v9
	v_and_b32_e32 v2, 0xfc, v2
	v_cmp_lt_i32_e32 vcc, s31, v4
	v_lshlrev_b64 v[8:9], 12, v[4:5]
	v_lshlrev_b32_e32 v18, 2, v2
	v_cndmask_b32_e32 v6, v29, v6, vcc
	s_waitcnt lgkmcnt(0)
	s_add_u32 s28, s2, 0x1000
	v_lshlrev_b64 v[4:5], 11, v[4:5]
	v_lshl_add_u64 v[8:9], s[4:5], 0, v[8:9]
	v_mov_b32_e32 v3, v19
	v_lshlrev_b32_e32 v106, 2, v7
	v_lshlrev_b32_e32 v2, 1, v2
	v_ashrrev_i32_e32 v7, 31, v6
	s_addc_u32 s29, s3, 0
	v_lshl_add_u64 v[4:5], s[6:7], 0, v[4:5]
	v_lshl_add_u64 v[8:9], v[8:9], 0, v[18:19]
	v_lshlrev_b32_e32 v109, 2, v10
	v_lshl_add_u64 v[6:7], v[6:7], 2, s[20:21]
	global_load_dwordx4 v[38:41], v18, s[28:29]
	v_lshl_add_u64 v[22:23], v[4:5], 0, v[2:3]
	global_load_dwordx4 v[42:45], v[8:9], off
	global_load_dwordx4 v[46:49], v[8:9], off offset:1024
	global_load_dwordx4 v[10:13], v[8:9], off offset:2048
	global_load_dwordx4 v[2:5], v[8:9], off offset:3072
	v_add_co_u32_e32 v68, vcc, s33, v8
	v_lshl_add_u64 v[26:27], v[6:7], 0, s[24:25]
	v_lshl_add_u64 v[24:25], v[6:7], 0, s[14:15]
	v_addc_co_u32_e32 v69, vcc, 0, v9, vcc
	v_lshl_add_u64 v[70:71], v[26:27], 0, v[18:19]
	v_lshl_add_u64 v[72:73], v[24:25], 0, v[18:19]
	global_load_dwordx4 v[50:53], v[68:69], off
	global_load_dwordx4 v[54:57], v[68:69], off offset:1024
	global_load_dwordx4 v[14:17], v[68:69], off offset:2048
	global_load_dwordx4 v[6:9], v[68:69], off offset:3072
	global_load_dwordx4 v[58:61], v[72:73], off
	global_load_dwordx4 v[62:65], v[70:71], off
	v_mov_b32_e32 v115, v19
	v_or_b32_e32 v114, 0x400, v18
	v_lshl_add_u64 v[116:117], v[24:25], 0, v[114:115]
	global_load_dwordx4 v[118:121], v[116:117], off
	v_mov_b32_e32 v115, v19
	v_or_b32_e32 v114, 0x400, v18
	v_lshl_add_u64 v[122:123], v[26:27], 0, v[114:115]
	global_load_dwordx4 v[124:127], v[122:123], off
	v_or_b32_e32 v114, 0x400, v18
	global_load_dwordx4 v[128:131], v114, s[28:29]
	v_mov_b32_e32 v133, v19
	v_or_b32_e32 v132, 0x800, v18
	v_lshl_add_u64 v[134:135], v[24:25], 0, v[132:133]
	global_load_dwordx4 v[136:139], v[134:135], off
	v_mov_b32_e32 v133, v19
	v_or_b32_e32 v132, 0x800, v18
	v_lshl_add_u64 v[140:141], v[26:27], 0, v[132:133]
	global_load_dwordx4 v[142:145], v[140:141], off
	v_or_b32_e32 v132, 0x800, v18
	global_load_dwordx4 v[146:149], v132, s[28:29]
	v_or_b32_e32 v150, 0xc00, v18
	v_mov_b32_e32 v151, v19
	v_lshl_add_u64 v[152:153], v[24:25], 0, v[150:151]
	global_load_dwordx4 v[154:157], v[152:153], off
	v_or_b32_e32 v150, 0xc00, v18
	v_mov_b32_e32 v151, v19
	v_lshl_add_u64 v[158:159], v[26:27], 0, v[150:151]
	global_load_dwordx4 v[160:163], v[158:159], off
	v_or_b32_e32 v150, 0xc00, v18
	global_load_dwordx4 v[164:167], v150, s[28:29]
	v_mov_b32_e32 v67, v19
	v_or_b32_e32 v66, 0x400, v18
	v_lshl_add_u64 v[74:75], v[26:27], 0, v[66:67]
	v_lshl_add_u64 v[76:77], v[24:25], 0, v[66:67]
	v_add_u32_e32 v1, s11, v1
	s_waitcnt vmcnt(18)
	v_mov_b32_e32 v70, v43
	s_waitcnt vmcnt(17)
	v_mov_b32_e32 v71, v47
	s_waitcnt vmcnt(16)
	v_mov_b32_e32 v82, v11
	s_waitcnt vmcnt(15)
	v_mov_b32_e32 v83, v3
	v_mov_b32_e32 v68, v42
	v_mov_b32_e32 v69, v46
	v_mov_b32_e32 v80, v10
	s_waitcnt vmcnt(14)
	v_mov_b32_e32 v90, v51
	s_waitcnt vmcnt(13)
	v_mov_b32_e32 v91, v55
	v_mov_b32_e32 v81, v2
	v_pk_mul_f32 v[70:71], v[70:71], v[70:71]
	v_mov_b32_e32 v88, v50
	v_mov_b32_e32 v89, v54
	v_pk_mul_f32 v[82:83], v[82:83], v[82:83]
	s_waitcnt vmcnt(12)
	v_mov_b32_e32 v98, v15
	s_waitcnt vmcnt(11)
	v_mov_b32_e32 v99, v7
	s_waitcnt vmcnt(10)
	v_add_f32_e32 v111, 1.0, v60
	v_add_f32_e32 v112, 1.0, v61
	v_pk_mul_f32 v[60:61], v[90:91], v[90:91]
	v_mov_b32_e32 v72, v44
	v_mov_b32_e32 v73, v48
	v_mov_b32_e32 v92, v52
	v_mov_b32_e32 v93, v56
	v_mov_b32_e32 v96, v14
	v_mov_b32_e32 v97, v6
	v_add_f32_e32 v67, 1.0, v58
	v_add_f32_e32 v110, 1.0, v59
	v_pk_fma_f32 v[58:59], v[68:69], v[68:69], v[70:71]
	v_pk_fma_f32 v[68:69], v[80:81], v[80:81], v[82:83]
	v_pk_mul_f32 v[70:71], v[98:99], v[98:99]
	v_mul_f32_e32 v81, v40, v111
	v_mul_f32_e32 v82, v41, v112
	v_pk_fma_f32 v[40:41], v[88:89], v[88:89], v[60:61]
	v_mov_b32_e32 v78, v45
	v_mov_b32_e32 v79, v49
	v_mov_b32_e32 v84, v12
	v_mov_b32_e32 v85, v4
	v_mov_b32_e32 v94, v53
	v_mov_b32_e32 v95, v57
	v_mov_b32_e32 v100, v16
	v_mov_b32_e32 v101, v8
	v_mul_f32_e32 v67, v38, v67
	v_mul_f32_e32 v80, v39, v110
	v_pk_fma_f32 v[38:39], v[72:73], v[72:73], v[58:59]
	v_pk_fma_f32 v[60:61], v[96:97], v[96:97], v[70:71]
	v_pk_fma_f32 v[40:41], v[92:93], v[92:93], v[40:41]
	v_mov_b32_e32 v86, v13
	v_mov_b32_e32 v87, v5
	v_mov_b32_e32 v102, v17
	v_mov_b32_e32 v103, v9
	v_pk_fma_f32 v[58:59], v[84:85], v[84:85], v[68:69]
	v_pk_fma_f32 v[38:39], v[78:79], v[78:79], v[38:39]
	v_pk_fma_f32 v[60:61], v[100:101], v[100:101], v[60:61]
	v_pk_fma_f32 v[40:41], v[94:95], v[94:95], v[40:41]
	v_pk_fma_f32 v[58:59], v[86:87], v[86:87], v[58:59]
	v_pk_fma_f32 v[60:61], v[102:103], v[102:103], v[60:61]
	v_mov_b32_e32 v69, v38
	v_mov_b32_e32 v68, v40
	v_mov_b32_e32 v38, v41
	v_mov_b32_e32 v71, v58
	v_mov_b32_e32 v70, v60
	v_pk_add_f32 v[38:39], v[68:69], v[38:39]
	v_mov_b32_e32 v58, v61
	v_pk_add_f32 v[38:39], v[38:39], v[70:71]
	s_nop 0
	v_pk_add_f32 v[38:39], v[38:39], v[58:59]
	ds_bpermute_b32 v41, v104, v39
	ds_bpermute_b32 v40, v104, v38
	v_mov_b32_e32 v59, v19
	v_or_b32_e32 v58, 0x800, v18
	v_lshl_add_u64 v[60:61], v[26:27], 0, v[58:59]
	v_or_b32_e32 v18, 0xc00, v18
	s_waitcnt lgkmcnt(0)
	v_pk_add_f32 v[38:39], v[38:39], v[40:41]
	ds_bpermute_b32 v41, v105, v39
	ds_bpermute_b32 v40, v105, v38
	s_waitcnt lgkmcnt(0)
	v_pk_add_f32 v[38:39], v[38:39], v[40:41]
	ds_bpermute_b32 v41, v106, v39
	ds_bpermute_b32 v40, v106, v38
	s_waitcnt lgkmcnt(0)
	v_pk_add_f32 v[38:39], v[38:39], v[40:41]
	ds_bpermute_b32 v41, v107, v39
	ds_bpermute_b32 v40, v107, v38
	s_waitcnt lgkmcnt(0)
	v_pk_add_f32 v[38:39], v[38:39], v[40:41]
	ds_bpermute_b32 v41, v108, v39
	ds_bpermute_b32 v40, v108, v38
	s_waitcnt lgkmcnt(0)
	v_pk_add_f32 v[38:39], v[38:39], v[40:41]
	ds_bpermute_b32 v41, v109, v39
	ds_bpermute_b32 v40, v109, v38
	s_waitcnt lgkmcnt(0)
	v_pk_add_f32 v[38:39], v[38:39], v[40:41]
	s_nop 0
	v_pk_fma_f32 v[38:39], v[38:39], s[26:27], v[20:21] op_sel_hi:[1,0,0]
	v_add_u32_e32 v21, s27, v21
	v_mul_f32_e32 v40, 0x4b800000, v39
	v_cmp_gt_f32_e64 s[2:3], s34, v39
	v_mul_f32_e32 v41, 0x4b800000, v38
	v_cmp_gt_f32_e32 vcc, s34, v38
	v_cndmask_b32_e64 v39, v39, v40, s[2:3]
	v_rsq_f32_e32 v39, v39
	v_cndmask_b32_e32 v38, v38, v41, vcc
	v_rsq_f32_e32 v38, v38
	v_mul_f32_e32 v40, 0x45800000, v39
	v_cndmask_b32_e64 v68, v39, v40, s[2:3]
	v_mul_f32_e32 v41, 0x45800000, v38
	v_cndmask_b32_e32 v69, v38, v41, vcc
	v_mul_f32_e32 v38, v42, v68
	v_mul_f32_e32 v39, v43, v68
	v_mul_f32_e32 v40, v44, v68
	v_mul_f32_e32 v41, v45, v68
	s_waitcnt vmcnt(9)
	v_fma_f32 v38, v38, v67, v62
	v_fma_f32 v39, v39, v80, v63
	v_mul_f32_e32 v42, v50, v69
	v_mul_f32_e32 v43, v51, v69
	v_mul_f32_e32 v44, v52, v69
	v_mul_f32_e32 v45, v53, v69
	v_fma_f32 v40, v40, v81, v64
	v_fma_f32 v41, v41, v82, v65
	v_cvt_pk_bf16_f32 v38, v38, v39
	v_cvt_pk_bf16_f32 v39, v40, v41
	v_fma_f32 v42, v42, v67, v62
	v_fma_f32 v43, v43, v80, v63
	v_fma_f32 v44, v44, v81, v64
	v_fmac_f32_e32 v65, v45, v82
	v_cvt_pk_bf16_f32 v40, v42, v43
	v_cvt_pk_bf16_f32 v41, v44, v65
	global_store_dwordx2 v[22:23], v[38:39], off
	global_store_dwordx2 v[22:23], v[40:41], off offset:2048
	s_nop 0
	v_mul_f32_e32 v46, v46, v68
	v_mul_f32_e32 v47, v47, v68
	v_mul_f32_e32 v48, v48, v68
	v_mul_f32_e32 v49, v49, v68
	v_mul_f32_e32 v54, v54, v69
	v_mul_f32_e32 v55, v55, v69
	v_mul_f32_e32 v56, v56, v69
	v_mul_f32_e32 v57, v57, v69
	v_lshl_add_u64 v[62:63], v[24:25], 0, v[58:59]
	v_mul_f32_e32 v10, v10, v68
	v_mul_f32_e32 v11, v11, v68
	v_mul_f32_e32 v12, v12, v68
	v_mul_f32_e32 v13, v13, v68
	v_mul_f32_e32 v14, v14, v69
	v_mul_f32_e32 v15, v15, v69
	v_mul_f32_e32 v16, v16, v69
	v_mul_f32_e32 v17, v17, v69
	v_mul_f32_e32 v2, v2, v68
	v_mul_f32_e32 v3, v3, v68
	v_cmp_lt_i32_e32 vcc, s35, v1
	v_mul_f32_e32 v4, v4, v68
	v_mul_f32_e32 v5, v5, v68
	s_or_b64 s[22:23], vcc, s[22:23]
	v_mul_f32_e32 v6, v6, v69
	v_mul_f32_e32 v7, v7, v69
	v_mul_f32_e32 v8, v8, v69
	v_mul_f32_e32 v9, v9, v69
	s_waitcnt vmcnt(10)
	v_add_f32_e32 v118, 1.0, v118
	v_add_f32_e32 v119, 1.0, v119
	v_add_f32_e32 v120, 1.0, v120
	v_add_f32_e32 v121, 1.0, v121
	s_waitcnt vmcnt(8)
	v_mul_f32_e32 v118, v128, v118
	v_mul_f32_e32 v119, v129, v119
	v_mul_f32_e32 v120, v130, v120
	v_mul_f32_e32 v121, v131, v121
	v_fma_f32 v46, v46, v118, v124
	v_fma_f32 v47, v47, v119, v125
	v_fma_f32 v48, v48, v120, v126
	v_fma_f32 v49, v49, v121, v127
	v_fma_f32 v124, v54, v118, v124
	v_fma_f32 v125, v55, v119, v125
	v_cvt_pk_bf16_f32 v38, v46, v47
	v_cvt_pk_bf16_f32 v39, v48, v49
	v_fma_f32 v126, v56, v120, v126
	v_fmac_f32_e32 v127, v57, v121
	v_cvt_pk_bf16_f32 v40, v124, v125
	v_cvt_pk_bf16_f32 v41, v126, v127
	global_store_dwordx2 v[22:23], v[38:39], off offset:512
	global_store_dwordx2 v[22:23], v[40:41], off offset:2560
	s_nop 0
	v_lshl_add_u64 v[52:53], v[24:25], 0, v[18:19]
	v_lshl_add_u64 v[50:51], v[26:27], 0, v[18:19]
	s_waitcnt vmcnt(9)
	v_add_f32_e32 v24, 1.0, v136
	v_add_f32_e32 v25, 1.0, v137
	v_add_f32_e32 v26, 1.0, v138
	v_add_f32_e32 v27, 1.0, v139
	s_waitcnt vmcnt(7)
	v_mul_f32_e32 v24, v146, v24
	v_mul_f32_e32 v25, v147, v25
	v_mul_f32_e32 v26, v148, v26
	v_mul_f32_e32 v27, v149, v27
	v_fma_f32 v10, v10, v24, v142
	v_fma_f32 v11, v11, v25, v143
	v_fma_f32 v12, v12, v26, v144
	v_fma_f32 v13, v13, v27, v145
	v_cvt_pk_bf16_f32 v10, v10, v11
	v_cvt_pk_bf16_f32 v11, v12, v13
	v_fma_f32 v14, v14, v24, v142
	v_fma_f32 v15, v15, v25, v143
	v_fma_f32 v16, v16, v26, v144
	v_fmac_f32_e32 v145, v17, v27
	v_cvt_pk_bf16_f32 v12, v14, v15
	v_cvt_pk_bf16_f32 v13, v16, v145
	global_store_dwordx2 v[22:23], v[10:11], off offset:1024
	global_store_dwordx2 v[22:23], v[12:13], off offset:3072
	s_nop 0
	s_waitcnt vmcnt(8)
	v_add_f32_e32 v154, 1.0, v154
	v_add_f32_e32 v155, 1.0, v155
	v_add_f32_e32 v156, 1.0, v156
	v_add_f32_e32 v157, 1.0, v157
	s_waitcnt vmcnt(6)
	v_mul_f32_e32 v154, v164, v154
	v_mul_f32_e32 v155, v165, v155
	v_mul_f32_e32 v156, v166, v156
	v_mul_f32_e32 v157, v167, v157
	v_fma_f32 v2, v2, v154, v160
	v_fma_f32 v3, v3, v155, v161
	v_fma_f32 v4, v4, v156, v162
	v_fma_f32 v5, v5, v157, v163
	v_cvt_pk_bf16_f32 v2, v2, v3
	v_cvt_pk_bf16_f32 v3, v4, v5
	v_fma_f32 v6, v6, v154, v160
	v_fma_f32 v7, v7, v155, v161
	v_fma_f32 v8, v8, v156, v162
	v_fmac_f32_e32 v163, v9, v157
	v_cvt_pk_bf16_f32 v4, v6, v7
	v_cvt_pk_bf16_f32 v5, v8, v163
	global_store_dwordx2 v[22:23], v[2:3], off offset:1536
	global_store_dwordx2 v[22:23], v[4:5], off offset:3584
	s_andn2_b64 exec, exec, s[22:23]
	s_cbranch_execnz .LBB0_2322

.LBB0_2541:
	s_mov_b32 s98, 0
	v_mov_b32_e32 v255, 0x0
	v_bfe_u32 v1, v0, 0, 1
	v_lshlrev_b32_e32 v1, 7, v1
	v_xor_b32_e32 v255, v255, v1
	v_bfe_u32 v1, v0, 1, 3
	v_mul_u32_u24_e32 v1, 0x110, v1
	v_xor_b32_e32 v255, v255, v1
	v_bfe_u32 v1, v0, 4, 2
	v_lshlrev_b32_e32 v1, 4, v1
	v_xor_b32_e32 v255, v255, v1
	v_bfe_u32 v1, v0, 8, 1
	v_lshlrev_b32_e32 v1, 14, v1
	v_xor_b32_e32 v255, v255, v1
	v_add_u32_e32 v254, 0x10000, v255
	v_xor_b32_e32 v253, 0x880, v255
	v_xor_b32_e32 v252, 0x10880, v255
	v_mov_b32_e32 v251, 0x8000
	v_bfe_u32 v1, v0, 0, 1
	v_lshlrev_b32_e32 v1, 7, v1
	v_xor_b32_e32 v251, v251, v1
	v_bfe_u32 v1, v0, 1, 3
	v_mul_u32_u24_e32 v1, 0x110, v1
	v_xor_b32_e32 v251, v251, v1
	v_bfe_u32 v1, v0, 4, 2
	v_lshlrev_b32_e32 v1, 4, v1
	v_xor_b32_e32 v251, v251, v1
	v_bfe_u32 v1, v0, 6, 2
	v_lshlrev_b32_e32 v1, 13, v1
	v_xor_b32_e32 v251, v251, v1
	v_add_u32_e32 v250, 0x10000, v251
	v_xor_b32_e32 v249, 0x880, v251
	v_xor_b32_e32 v248, 0x10880, v251
	v_xor_b32_e32 v247, 0x40, v255
	v_xor_b32_e32 v246, 0x10040, v255
	v_xor_b32_e32 v245, 0x8c0, v255
	v_xor_b32_e32 v244, 0x108c0, v255
	v_xor_b32_e32 v243, 0x40, v251
	v_xor_b32_e32 v242, 0x10040, v251
	v_xor_b32_e32 v241, 0x8c0, v251
	v_xor_b32_e32 v237, 0x108c0, v251
	v_mov_b32_e32 v236, 0x0
	v_bfe_u32 v1, v0, 0, 4
	v_lshlrev_b32_e32 v1, 4, v1
	v_xor_b32_e32 v236, v236, v1
	v_bfe_u32 v1, v0, 4, 4
	v_mul_u32_u24_e32 v1, 0x110, v1
	v_xor_b32_e32 v236, v236, v1
	v_bfe_u32 v1, v0, 8, 1
	v_lshlrev_b32_e32 v1, 12, v1
	v_xor_b32_e32 v236, v236, v1
	v_add_u32_e32 v235, 0x10000, v236
	v_mov_b32_e32 v234, 0x0
	v_bfe_u32 v1, v0, 0, 3
	v_lshlrev_b32_e32 v1, 4, v1
	v_add_u32_e32 v234, v234, v1
	v_bfe_u32 v1, v0, 3, 6
	v_mul_u32_u24_e32 v1, 0x1600, v1
	v_add_u32_e32 v234, v234, v1
	v_add_u32_e32 v233, 0x58000, v234
	v_add_u32_e32 v232, 0xb0000, v234
	v_add_u32_e32 v231, 0x108000, v234
	v_mov_b32_e32 v1, v0
	s_load_dword s0, s[0:1], 0xe0
	s_mov_b32 s1, s10
	v_mov_b32_e32 v1, v0
	s_waitcnt lgkmcnt(0)
	s_lshr_b32 s11, s0, 3
	s_waitcnt vmcnt(0)
	v_cvt_f32_u32_e32 v2, s11
	s_mov_b32 s0, s10
	s_ashr_i32 s1, s0, 3
	v_rcp_iflag_f32_e32 v2, v2
	s_ashr_i32 s2, s0, 31
	s_sub_i32 s0, 0, s11
	s_abs_i32 s1, s1
	v_mul_f32_e32 v1, 0x4f7ffffe, v2
	v_cvt_u32_f32_e32 v1, v1
	s_mov_b32 s42, 0
	v_readfirstlane_b32 s3, v1
	s_mul_i32 s0, s0, s3
	s_mul_hi_u32 s0, s3, s0
	s_add_i32 s0, s3, s0
	s_mul_hi_u32 s3, s1, s0
	s_mul_i32 s3, s3, s11
	s_sub_i32 s1, s1, s3
	s_sub_i32 s3, s1, s11
	s_cmp_ge_u32 s1, s11
	s_cselect_b32 s1, s3, s1
	s_sub_i32 s3, s1, s11
	s_cmp_ge_u32 s1, s11
	s_cselect_b32 s1, s3, s1
	s_xor_b32 s1, s1, s2
	s_sub_i32 s20, s1, s2
	s_mov_b32 s1, s10
	s_cmp_gt_i32 s20, 31
	s_cbranch_scc1 .LBB0_2605
	s_load_dwordx4 s[4:7], s[16:17], 0xc8
	s_mov_b32 s1, s10
	v_mov_b32_e32 v82, 0
	v_mov_b32_e32 v1, v0
	s_waitcnt lgkmcnt(0)
	s_add_u32 s2, s4, 0x2000000
	s_addc_u32 s3, s5, 0
	s_add_u32 s8, s6, 0x27000
	s_addc_u32 s9, s7, 0
	s_add_u32 s21, s6, 0x37f0000
	s_addc_u32 s22, s7, 0
	s_add_u32 s23, s6, 0x1270000
	s_addc_u32 s24, s7, 0
	s_ashr_i32 s6, s20, 31
	s_lshr_b32 s6, s6, 27
	s_add_i32 s6, s20, s6
	s_ashr_i32 s6, s6, 5
	s_lshl_b32 s7, s20, 1
	s_lshl_b32 s12, s6, 6
	s_sub_i32 s7, s7, s12
	s_lshl_b32 s6, s6, 2
	s_and_b32 s12, s20, 3
	s_or_b32 s25, s6, s12
	s_sub_i32 s6, s11, s20
	s_add_i32 s6, s6, 31
	s_mul_hi_u32 s0, s6, s0
	s_mul_i32 s12, s0, s11
	s_sub_i32 s6, s6, s12
	s_add_i32 s12, s0, 1
	s_sub_i32 s13, s6, s11
	s_cmp_ge_u32 s6, s11
	s_cselect_b32 s0, s12, s0
	s_cselect_b32 s6, s13, s6
	s_add_i32 s12, s0, 1
	s_cmp_ge_u32 s6, s11
	s_cselect_b32 s33, s12, s0
	s_and_b32 s0, s1, 7
	s_and_b32 s1, s7, -8
	s_movk_i32 s26, 0xb00
	v_lshrrev_b32_e32 v2, 3, v1
	s_or_b32 s27, s0, s1
	s_lshl_b32 s0, s25, 8
	s_mul_i32 s1, s25, 0x160000
	v_mul_lo_u32 v2, v2, s26
	v_lshlrev_b32_e32 v1, 3, v1
	s_mul_hi_i32 s6, s0, 0x1600
	s_add_u32 s0, s23, s1
	v_and_or_b32 v1, v1, 56, v2
	v_mov_b32_e32 v239, 0
	s_addc_u32 s1, s24, s6
	v_lshlrev_b32_e32 v238, 1, v1
	v_lshl_add_u64 v[2:3], s[0:1], 0, v[238:239]
	s_mov_b32 s28, 0x108000
	v_add_co_u32_e32 v34, vcc, s28, v2
	s_mov_b32 s12, 0xb0000
	s_nop 0
	v_addc_co_u32_e32 v35, vcc, 0, v3, vcc
	v_add_co_u32_e32 v36, vcc, s12, v2
	s_lshl_b32 s6, s27, 8
	s_mul_i32 s7, s27, 0x160000
	v_addc_co_u32_e32 v37, vcc, 0, v3, vcc
	s_mov_b32 s29, 0x58000
	s_mul_hi_i32 s13, s6, 0x1600
	s_add_u32 s6, s21, s7
	v_add_co_u32_e32 v2, vcc, s29, v2
	s_addc_u32 s7, s22, s13
	s_nop 0
	v_addc_co_u32_e32 v3, vcc, 0, v3, vcc
	v_lshl_add_u64 v[22:23], s[6:7], 0, v[238:239]
	v_add_co_u32_e32 v24, vcc, s12, v22
	global_load_dwordx4 v[2:5], v[2:3], off
	s_nop 0
	v_addc_co_u32_e32 v25, vcc, 0, v23, vcc
	v_add_co_u32_e32 v26, vcc, s29, v22
	v_mov_b32_e32 v1, v0
	s_nop 0
	v_addc_co_u32_e32 v27, vcc, 0, v23, vcc
	v_add_co_u32_e32 v38, vcc, s28, v22
	global_load_dwordx4 v[6:9], v[24:25], off
	global_load_dwordx4 v[10:13], v[26:27], off
	global_load_dwordx4 v[14:17], v238, s[0:1]
	global_load_dwordx4 v[18:21], v238, s[6:7]
	v_addc_co_u32_e32 v39, vcc, 0, v23, vcc
	global_load_dwordx4 v[22:25], v[38:39], off
	global_load_dwordx4 v[26:29], v[36:37], off
	global_load_dwordx4 v[30:33], v[34:35], off
	s_movk_i32 s31, 0xf0
	v_ashrrev_i32_e32 v34, 4, v1
	v_xor_b32_e32 v1, v34, v1
	v_lshlrev_b32_e32 v34, 8, v34
	v_lshlrev_b32_e32 v1, 4, v1
	v_and_or_b32 v1, v1, s31, v34
	s_mov_b32 s30, 2
	s_mul_i32 s33, s33, 44
	s_movk_i32 s34, 0xff80
	s_mov_b32 s35, 0x10000
	s_mov_b32 s36, 0x11000
	s_movk_i32 s37, 0x1800
	s_movk_i32 s38, 0x1fff
	v_mov_b32_e32 v240, 0x8040
	s_mov_b32 s18, 2
	s_mov_b32 s39, s20
	s_mov_b32 s40, s25
	s_mov_b32 s41, s27
	v_mov_b32_e32 v83, v82
	v_mov_b32_e32 v84, v82
	v_mov_b32_e32 v85, v82
	v_mov_b32_e32 v102, v82
	v_mov_b32_e32 v103, v82
	v_mov_b32_e32 v104, v82
	v_mov_b32_e32 v105, v82
	v_mov_b32_e32 v106, v82
	v_mov_b32_e32 v107, v82
	v_mov_b32_e32 v108, v82
	v_mov_b32_e32 v109, v82
	v_mov_b32_e32 v110, v82
	v_mov_b32_e32 v111, v82
	v_mov_b32_e32 v112, v82
	v_mov_b32_e32 v113, v82
	s_waitcnt vmcnt(4)
	ds_write_b128 v1, v[14:17] offset:32768
	s_waitcnt vmcnt(3)
	ds_write_b128 v1, v[18:21]
	ds_write_b128 v1, v[2:5] offset:40960
	ds_write_b128 v1, v[10:13] offset:8192
	ds_write_b128 v1, v[6:9] offset:16384
	s_waitcnt vmcnt(2)
	ds_write_b128 v1, v[22:25] offset:24576
	s_waitcnt vmcnt(1)
	ds_write_b128 v1, v[26:29] offset:49152
	s_waitcnt vmcnt(0)
	ds_write_b128 v1, v[30:33] offset:57344
	v_mov_b32_e32 v1, v0
	v_mov_b32_e32 v114, v82
	v_lshrrev_b32_e32 v2, 3, v1
	v_mul_lo_u32 v2, v2, s26
	v_lshlrev_b32_e32 v1, 3, v1
	v_and_or_b32 v1, v1, 56, v2
	v_lshlrev_b32_e32 v238, 1, v1
	v_lshl_add_u64 v[10:11], s[0:1], 0, v[238:239]
	v_add_co_u32_e32 v12, vcc, s28, v10
	v_lshl_add_u64 v[16:17], s[6:7], 0, v[238:239]
	s_nop 0
	v_addc_co_u32_e32 v13, vcc, 0, v11, vcc
	v_add_co_u32_e32 v14, vcc, s12, v10
	v_mov_b32_e32 v1, 0x10000
	s_nop 0
	v_addc_co_u32_e32 v15, vcc, 0, v11, vcc
	global_load_dwordx4 v[2:5], v[12:13], off offset:128
	global_load_dwordx4 v[6:9], v[14:15], off offset:128
	v_add_co_u32_e32 v14, vcc, s29, v10
	v_mov_b32_e32 v115, v82
	s_nop 0
	v_addc_co_u32_e32 v15, vcc, 0, v11, vcc
	v_add_co_u32_e32 v22, vcc, s28, v16
	v_mov_b32_e32 v116, v82
	s_nop 0
	v_addc_co_u32_e32 v23, vcc, 0, v17, vcc
	v_add_co_u32_e32 v34, vcc, s12, v16
	global_load_dwordx4 v[10:13], v[14:15], off offset:128
	global_load_dwordx4 v[18:21], v[22:23], off offset:128
	v_addc_co_u32_e32 v35, vcc, 0, v17, vcc
	v_add_co_u32_e32 v36, vcc, s29, v16
	v_mov_b32_e32 v117, v82
	s_nop 0
	v_addc_co_u32_e32 v37, vcc, 0, v17, vcc
	global_load_dwordx4 v[22:25], v[34:35], off offset:128
	global_load_dwordx4 v[26:29], v[36:37], off offset:128
	global_load_dwordx4 v[14:17], v238, s[0:1] offset:128
	global_load_dwordx4 v[30:33], v238, s[6:7] offset:128
	v_mov_b32_e32 v118, v82
	v_mov_b32_e32 v119, v82
	v_mov_b32_e32 v120, v82
	v_mov_b32_e32 v121, v82
	v_mov_b32_e32 v122, v82
	v_mov_b32_e32 v123, v82
	v_mov_b32_e32 v124, v82
	v_mov_b32_e32 v125, v82
	v_mov_b32_e32 v126, v82
	v_mov_b32_e32 v127, v82
	v_mov_b32_e32 v128, v82
	v_mov_b32_e32 v129, v82
	v_mov_b32_e32 v130, v82
	v_mov_b32_e32 v131, v82
	v_mov_b32_e32 v132, v82
	v_mov_b32_e32 v133, v82
	v_mov_b32_e32 v134, v82
	v_mov_b32_e32 v135, v82
	v_mov_b32_e32 v136, v82
	v_mov_b32_e32 v137, v82
	v_mov_b32_e32 v138, v82
	v_mov_b32_e32 v139, v82
	v_mov_b32_e32 v140, v82
	v_mov_b32_e32 v141, v82
	v_mov_b32_e32 v142, v82
	v_mov_b32_e32 v143, v82
	v_mov_b32_e32 v144, v82
	v_mov_b32_e32 v145, v82
	v_mov_b32_e32 v146, v82
	v_mov_b32_e32 v147, v82
	v_mov_b32_e32 v148, v82
	v_mov_b32_e32 v149, v82
	v_mov_b32_e32 v150, v82
	v_mov_b32_e32 v151, v82
	v_mov_b32_e32 v152, v82
	v_mov_b32_e32 v153, v82
	v_mov_b32_e32 v154, v82
	v_mov_b32_e32 v155, v82
	v_mov_b32_e32 v156, v82
	v_mov_b32_e32 v157, v82
	v_mov_b32_e32 v158, v82
	v_mov_b32_e32 v159, v82
	v_mov_b32_e32 v160, v82
	v_mov_b32_e32 v161, v82
	v_mov_b32_e32 v98, v82
	v_mov_b32_e32 v99, v82
	v_mov_b32_e32 v100, v82
	v_mov_b32_e32 v101, v82
	v_mov_b32_e32 v94, v82
	v_mov_b32_e32 v95, v82
	v_mov_b32_e32 v96, v82
	v_mov_b32_e32 v97, v82
	v_mov_b32_e32 v90, v82
	v_mov_b32_e32 v91, v82
	v_mov_b32_e32 v92, v82
	v_mov_b32_e32 v93, v82
	v_mov_b32_e32 v86, v82
	v_mov_b32_e32 v87, v82
	v_mov_b32_e32 v88, v82
	v_mov_b32_e32 v89, v82
	v_mov_b32_e32 v78, v82
	v_mov_b32_e32 v79, v82
	v_mov_b32_e32 v80, v82
	v_mov_b32_e32 v81, v82
	v_mov_b32_e32 v74, v82
	v_mov_b32_e32 v75, v82
	v_mov_b32_e32 v76, v82
	v_mov_b32_e32 v77, v82
	v_mov_b32_e32 v70, v82
	v_mov_b32_e32 v71, v82
	v_mov_b32_e32 v72, v82
	v_mov_b32_e32 v73, v82
	v_mov_b32_e32 v66, v82
	v_mov_b32_e32 v67, v82
	v_mov_b32_e32 v68, v82
	v_mov_b32_e32 v69, v82
	v_mov_b32_e32 v62, v82
	v_mov_b32_e32 v63, v82
	v_mov_b32_e32 v64, v82
	v_mov_b32_e32 v65, v82
	v_mov_b32_e32 v58, v82
	v_mov_b32_e32 v59, v82
	v_mov_b32_e32 v60, v82
	v_mov_b32_e32 v61, v82
	v_mov_b32_e32 v54, v82
	v_mov_b32_e32 v55, v82
	v_mov_b32_e32 v56, v82
	v_mov_b32_e32 v57, v82
	v_mov_b32_e32 v50, v82
	v_mov_b32_e32 v51, v82
	v_mov_b32_e32 v52, v82
	v_mov_b32_e32 v53, v82
	v_mov_b32_e32 v46, v82
	v_mov_b32_e32 v47, v82
	v_mov_b32_e32 v48, v82
	v_mov_b32_e32 v49, v82
	v_mov_b32_e32 v42, v82
	v_mov_b32_e32 v43, v82
	v_mov_b32_e32 v44, v82
	v_mov_b32_e32 v45, v82
	v_mov_b32_e32 v38, v82
	v_mov_b32_e32 v39, v82
	v_mov_b32_e32 v40, v82
	v_mov_b32_e32 v41, v82
	v_mov_b32_e32 v34, v82
	v_mov_b32_e32 v35, v82
	v_mov_b32_e32 v36, v82
	v_mov_b32_e32 v37, v82
	s_waitcnt lgkmcnt(0)
	s_barrier
	s_waitcnt vmcnt(0)
	s_branch .LBB0_2545
